# GEMM main loops: dropped the second of two back-to-back lgkmcnt(0) waits in each MFMA phase
# speedup vs baseline: 1.0226x; 1.0125x over previous
; #define PG8_STAGE(bufoff, gbase, voff) do { _Pragma("unroll") for (int _i = 0; _i < 2; ++_i) \
;         __builtin_amdgcn_global_load_lds((const unsigned*)((const char*)(gbase) + (voff)[_i]), (LAS unsigned*)(lds + (bufoff) + ldsw + _i * 8192), 16, 0, 0); } while (0)
; #define PG8_LDA(dst, b, h) do { _Pragma("unroll") for (int m = 0; m < 4; ++m) _Pragma("unroll") for (int k = 0; k < 2; ++k) dst[m][k] = *(const LAS bf16x8*)(lds + PG8_SA(b, h) + aoff + m * 2048 + k * 1024); } while (0)
; #define PG8_LDB(dst, b, h) do { _Pragma("unroll") for (int n = 0; n < 2; ++n) _Pragma("unroll") for (int k = 0; k < 2; ++k) dst[n][k] = *(const LAS bf16x8*)(lds + PG8_SB(b, h) + boff + n * 2048 + k * 1024); } while (0)
; #define PG8_MMA(ai, bj, At, Bt) do { __builtin_amdgcn_s_setprio(1); _Pragma("unroll") for (int m = 0; m < 4; ++m) _Pragma("unroll") for (int n = 0; n < 2; ++n) _Pragma("unroll") for (int k = 0; k < 2; ++k) \
;         acc[ai][bj][m][n] = __builtin_amdgcn_mfma_f32_16x16x32_bf16(Bt[n][k], At[m][k], acc[ai][bj][m][n], 0, 0, 0); __builtin_amdgcn_s_setprio(0); } while (0)
; #define PG8_WAIT_L(n) asm volatile("s_waitcnt lgkmcnt(" #n ")" ::: "memory")
; #define PG8_BAR __builtin_amdgcn_s_barrier()
; #define PG8_SCHED __builtin_amdgcn_sched_barrier(0)
; template <class Epi, class Sched>
; DI void gemm_phase(LAS unsigned char* lds, const Gemm g, const Sched& S, const Epi& E) {
;     ...
;             PG8_LDB(B0, 0, 0); PG8_SCHED; PG8_LDA(At, 0, 0); PG8_STAGE(PG8_SA(1, 1), a1 + hstep, voffA);
;             PG8_WAIT_L(8); PG8_BAR; PG8_WAIT_L(0); PG8_MMA(0, 0, At, B0); PG8_BAR; PG8_SCHED;
;             PG8_LDB(B1, 0, 1); PG8_STAGE(PG8_SB(0, 0), b2, voffB);
;             PG8_BAR; PG8_WAIT_L(0); PG8_MMA(0, 1, At, B1); PG8_BAR;
;             PG8_LDA(At, 0, 1); PG8_STAGE(PG8_SA(0, 0), a2, voffA);
;             PG8_BAR; PG8_WAIT_L(0); PG8_MMA(1, 0, At, B0); PG8_BAR; PG8_SCHED;
.LBB0_503:
	s_add_u32 s14, s8, 0xfffc0080
	s_addc_u32 s15, s9, -1
	s_add_i32 s75, 0, 0x10000
	v_add_u32_e32 v128, s75, v146
	ds_read_b128 v[140:143], v128
	ds_read_b128 v[178:181], v128 offset:1024
	ds_read_b128 v[182:185], v128 offset:2048
	ds_read_b128 v[186:189], v128 offset:3072
	s_cmp_eq_u32 s41, 12
	s_cselect_b32 s17, s11, s15
	s_cselect_b32 s16, s13, s14
	s_cselect_b32 s15, s35, s40
	s_cselect_b32 s14, s38, s39
	v_lshl_add_u64 v[144:145], s[8:9], 0, v[136:137]
	s_add_i32 m0, s66, 0xc000
	ds_read_b128 v[190:193], v148
	ds_read_b128 v[194:197], v148 offset:1024
	ds_read_b128 v[198:201], v148 offset:2048
	ds_read_b128 v[202:205], v148 offset:3072
	ds_read_b128 v[206:209], v148 offset:4096
	ds_read_b128 v[210:213], v148 offset:5120
	ds_read_b128 v[214:217], v148 offset:6144
	ds_read_b128 v[218:221], v148 offset:7168
	global_load_lds_dwordx4 v[144:145], off
	v_lshl_add_u64 v[144:145], s[8:9], 0, v[138:139]
	s_add_i32 m0, s66, 0xe000
	s_nop 0
	global_load_lds_dwordx4 v[144:145], off
	s_waitcnt lgkmcnt(8)
	s_barrier
	s_waitcnt lgkmcnt(0)
	s_setprio 1
	v_mfma_f32_16x16x32_bf16 v[124:127], v[140:143], v[190:193], v[124:127]
	v_mfma_f32_16x16x32_bf16 v[120:123], v[182:185], v[190:193], v[120:123]
	v_mfma_f32_16x16x32_bf16 v[108:111], v[140:143], v[198:201], v[108:111]
	v_mfma_f32_16x16x32_bf16 v[104:107], v[182:185], v[198:201], v[104:107]
	v_mfma_f32_16x16x32_bf16 v[92:95], v[140:143], v[206:209], v[92:95]
	v_mfma_f32_16x16x32_bf16 v[88:91], v[182:185], v[206:209], v[88:91]
	v_mfma_f32_16x16x32_bf16 v[76:79], v[140:143], v[214:217], v[76:79]
	v_mfma_f32_16x16x32_bf16 v[72:75], v[182:185], v[214:217], v[72:75]
	v_mfma_f32_16x16x32_bf16 v[124:127], v[178:181], v[194:197], v[124:127]
	v_mfma_f32_16x16x32_bf16 v[120:123], v[186:189], v[194:197], v[120:123]
	v_mfma_f32_16x16x32_bf16 v[108:111], v[178:181], v[202:205], v[108:111]
	v_mfma_f32_16x16x32_bf16 v[104:107], v[186:189], v[202:205], v[104:107]
	v_mfma_f32_16x16x32_bf16 v[92:95], v[178:181], v[210:213], v[92:95]
	v_mfma_f32_16x16x32_bf16 v[88:91], v[186:189], v[210:213], v[88:91]
	v_mfma_f32_16x16x32_bf16 v[76:79], v[178:181], v[218:221], v[76:79]
	v_mfma_f32_16x16x32_bf16 v[72:75], v[186:189], v[218:221], v[72:75]
	s_setprio 0
	s_barrier
	s_add_i32 s81, 0, 0x14000
	s_add_i32 s75, s75, s65
	v_add_u32_e32 v128, s81, v146
	v_lshl_add_u64 v[144:145], s[14:15], 0, v[132:133]
	s_mov_b32 m0, s75
	ds_read_b128 v[222:225], v128
	ds_read_b128 v[226:229], v128 offset:1024
	ds_read_b128 v[230:233], v128 offset:2048
	ds_read_b128 v[234:237], v128 offset:3072
	global_load_lds_dwordx4 v[144:145], off
	v_lshl_add_u64 v[150:151], s[14:15], 0, v[134:135]
	s_add_i32 m0, s75, 0x2000
	s_nop 0
	global_load_lds_dwordx4 v[150:151], off
	s_barrier
	s_waitcnt lgkmcnt(0)
	s_setprio 1
	v_mfma_f32_16x16x32_bf16 v[116:119], v[222:225], v[190:193], v[116:119]
	v_mfma_f32_16x16x32_bf16 v[112:115], v[230:233], v[190:193], v[112:115]
	v_mfma_f32_16x16x32_bf16 v[100:103], v[222:225], v[198:201], v[100:103]
	v_mfma_f32_16x16x32_bf16 v[96:99], v[230:233], v[198:201], v[96:99]
	v_mfma_f32_16x16x32_bf16 v[84:87], v[222:225], v[206:209], v[84:87]
	v_mfma_f32_16x16x32_bf16 v[80:83], v[230:233], v[206:209], v[80:83]
	v_mfma_f32_16x16x32_bf16 v[68:71], v[222:225], v[214:217], v[68:71]
	v_mfma_f32_16x16x32_bf16 v[64:67], v[230:233], v[214:217], v[64:67]
	v_mfma_f32_16x16x32_bf16 v[116:119], v[226:229], v[194:197], v[116:119]
	v_mfma_f32_16x16x32_bf16 v[112:115], v[234:237], v[194:197], v[112:115]
	v_mfma_f32_16x16x32_bf16 v[100:103], v[226:229], v[202:205], v[100:103]
	v_mfma_f32_16x16x32_bf16 v[96:99], v[234:237], v[202:205], v[96:99]
	v_mfma_f32_16x16x32_bf16 v[84:87], v[226:229], v[210:213], v[84:87]
	v_mfma_f32_16x16x32_bf16 v[80:83], v[234:237], v[210:213], v[80:83]
	v_mfma_f32_16x16x32_bf16 v[68:71], v[226:229], v[218:221], v[68:71]
	v_mfma_f32_16x16x32_bf16 v[64:67], v[234:237], v[218:221], v[64:67]
	s_setprio 0
	s_mov_b32 m0, s66
	v_lshl_add_u64 v[162:163], s[16:17], 0, v[132:133]
	s_barrier
	ds_read_b128 v[190:193], v148 offset:16384
	ds_read_b128 v[194:197], v148 offset:17408
	ds_read_b128 v[198:201], v148 offset:18432
	ds_read_b128 v[202:205], v148 offset:19456
	ds_read_b128 v[206:209], v148 offset:20480
	ds_read_b128 v[210:213], v148 offset:21504
	ds_read_b128 v[214:217], v148 offset:22528
	ds_read_b128 v[218:221], v148 offset:23552
	global_load_lds_dwordx4 v[162:163], off
	v_lshl_add_u64 v[238:239], s[16:17], 0, v[134:135]
	s_mov_b32 m0, s67
	s_nop 0
	global_load_lds_dwordx4 v[238:239], off
	s_barrier
	s_waitcnt lgkmcnt(0)
	s_setprio 1
	v_mfma_f32_16x16x32_bf16 v[60:63], v[140:143], v[190:193], v[60:63]
	v_mfma_f32_16x16x32_bf16 v[56:59], v[182:185], v[190:193], v[56:59]
	v_mfma_f32_16x16x32_bf16 v[44:47], v[140:143], v[198:201], v[44:47]
	v_mfma_f32_16x16x32_bf16 v[40:43], v[182:185], v[198:201], v[40:43]
	v_mfma_f32_16x16x32_bf16 v[28:31], v[140:143], v[206:209], v[28:31]
	v_mfma_f32_16x16x32_bf16 v[24:27], v[182:185], v[206:209], v[24:27]
	v_mfma_f32_16x16x32_bf16 v[12:15], v[140:143], v[214:217], v[12:15]
	v_mfma_f32_16x16x32_bf16 v[8:11], v[182:185], v[214:217], v[8:11]
	v_mfma_f32_16x16x32_bf16 v[60:63], v[178:181], v[194:197], v[60:63]
	v_mfma_f32_16x16x32_bf16 v[56:59], v[186:189], v[194:197], v[56:59]
	v_mfma_f32_16x16x32_bf16 v[44:47], v[178:181], v[202:205], v[44:47]
	v_mfma_f32_16x16x32_bf16 v[40:43], v[186:189], v[202:205], v[40:43]
	v_mfma_f32_16x16x32_bf16 v[28:31], v[178:181], v[210:213], v[28:31]
	v_mfma_f32_16x16x32_bf16 v[24:27], v[186:189], v[210:213], v[24:27]
	v_mfma_f32_16x16x32_bf16 v[12:15], v[178:181], v[218:221], v[12:15]
	v_mfma_f32_16x16x32_bf16 v[8:11], v[186:189], v[218:221], v[8:11]
	s_setprio 0
	s_barrier
; #define PG8_STAGE(bufoff, gbase, voff) do { _Pragma("unroll") for (int _i = 0; _i < 2; ++_i) \
;         __builtin_amdgcn_global_load_lds((const unsigned*)((const char*)(gbase) + (voff)[_i]), (LAS unsigned*)(lds + (bufoff) + ldsw + _i * 8192), 16, 0, 0); } while (0)
; #define PG8_LDA(dst, b, h) do { _Pragma("unroll") for (int m = 0; m < 4; ++m) _Pragma("unroll") for (int k = 0; k < 2; ++k) dst[m][k] = *(const LAS bf16x8*)(lds + PG8_SA(b, h) + aoff + m * 2048 + k * 1024); } while (0)
; #define PG8_LDB(dst, b, h) do { _Pragma("unroll") for (int n = 0; n < 2; ++n) _Pragma("unroll") for (int k = 0; k < 2; ++k) dst[n][k] = *(const LAS bf16x8*)(lds + PG8_SB(b, h) + boff + n * 2048 + k * 1024); } while (0)
; #define PG8_MMA(ai, bj, At, Bt) do { __builtin_amdgcn_s_setprio(1); _Pragma("unroll") for (int m = 0; m < 4; ++m) _Pragma("unroll") for (int n = 0; n < 2; ++n) _Pragma("unroll") for (int k = 0; k < 2; ++k) \
;         acc[ai][bj][m][n] = __builtin_amdgcn_mfma_f32_16x16x32_bf16(Bt[n][k], At[m][k], acc[ai][bj][m][n], 0, 0, 0); __builtin_amdgcn_s_setprio(0); } while (0)
; #define PG8_WAIT_V(n) asm volatile("s_waitcnt vmcnt(" #n ")" ::: "memory")
; #define PG8_WAIT_L(n) asm volatile("s_waitcnt lgkmcnt(" #n ")" ::: "memory")
; #define PG8_BAR __builtin_amdgcn_s_barrier()
; #define PG8_SCHED __builtin_amdgcn_sched_barrier(0)
; template <class Epi, class Sched>
; DI void gemm_phase(LAS unsigned char* lds, const Gemm g, const Sched& S, const Epi& E) {
;     ...
;             PG8_STAGE(PG8_SB(0, 1), b2 + hstep, voffB);
;             PG8_WAIT_V(6); PG8_BAR; PG8_MMA(1, 1, At, B1); PG8_BAR;
;             PG8_LDB(B0, 1, 0); PG8_SCHED; PG8_LDA(At, 1, 0); PG8_STAGE(PG8_SA(0, 1), a2 + hstep, voffA);
;             PG8_WAIT_L(8); PG8_BAR; PG8_WAIT_L(0); PG8_MMA(0, 0, At, B0); PG8_BAR; PG8_SCHED;
;             PG8_LDB(B1, 1, 1); PG8_STAGE(PG8_SB(1, 0), b3, voffB);
;             PG8_BAR; PG8_WAIT_L(0); PG8_MMA(0, 1, At, B1); PG8_BAR;
	s_add_u32 s92, s14, 0x40000
	s_addc_u32 s93, s15, 0
	s_add_i32 s75, s81, s65
	v_lshl_add_u64 v[140:141], s[92:93], 0, v[132:133]
	s_mov_b32 m0, s75
	s_nop 0
	global_load_lds_dwordx4 v[140:141], off
	v_lshl_add_u64 v[140:141], s[92:93], 0, v[134:135]
	s_add_i32 m0, s75, 0x2000
	s_nop 0
	global_load_lds_dwordx4 v[140:141], off
	s_waitcnt vmcnt(6)
	s_barrier
	s_setprio 1
	v_mfma_f32_16x16x32_bf16 v[52:55], v[222:225], v[190:193], v[52:55]
	v_mfma_f32_16x16x32_bf16 v[48:51], v[230:233], v[190:193], v[48:51]
	v_mfma_f32_16x16x32_bf16 v[36:39], v[222:225], v[198:201], v[36:39]
	v_mfma_f32_16x16x32_bf16 v[32:35], v[230:233], v[198:201], v[32:35]
	v_mfma_f32_16x16x32_bf16 v[20:23], v[222:225], v[206:209], v[20:23]
	v_mfma_f32_16x16x32_bf16 v[16:19], v[230:233], v[206:209], v[16:19]
	v_mfma_f32_16x16x32_bf16 v[4:7], v[222:225], v[214:217], v[4:7]
	v_mfma_f32_16x16x32_bf16 v[0:3], v[230:233], v[214:217], v[0:3]
	v_mfma_f32_16x16x32_bf16 v[52:55], v[226:229], v[194:197], v[52:55]
	v_mfma_f32_16x16x32_bf16 v[48:51], v[234:237], v[194:197], v[48:51]
	v_mfma_f32_16x16x32_bf16 v[36:39], v[226:229], v[202:205], v[36:39]
	v_mfma_f32_16x16x32_bf16 v[32:35], v[234:237], v[202:205], v[32:35]
	v_mfma_f32_16x16x32_bf16 v[20:23], v[226:229], v[210:213], v[20:23]
	v_mfma_f32_16x16x32_bf16 v[16:19], v[234:237], v[210:213], v[16:19]
	v_mfma_f32_16x16x32_bf16 v[4:7], v[226:229], v[218:221], v[4:7]
	v_mfma_f32_16x16x32_bf16 v[0:3], v[234:237], v[218:221], v[0:3]
	s_setprio 0
	s_add_i32 s75, 0, 0x18000
	v_add_u32_e32 v128, s75, v146
	s_barrier
	ds_read_b128 v[140:143], v128
	ds_read_b128 v[178:181], v128 offset:1024
	ds_read_b128 v[182:185], v128 offset:2048
	ds_read_b128 v[186:189], v128 offset:3072
	s_add_u32 s16, s16, 0x40000
	s_addc_u32 s17, s17, 0
	s_mov_b32 m0, s77
	v_lshl_add_u64 v[222:223], s[16:17], 0, v[132:133]
	ds_read_b128 v[190:193], v148 offset:32768
	ds_read_b128 v[194:197], v148 offset:33792
	ds_read_b128 v[198:201], v148 offset:34816
	ds_read_b128 v[202:205], v148 offset:35840
	ds_read_b128 v[206:209], v148 offset:36864
	ds_read_b128 v[210:213], v148 offset:37888
	ds_read_b128 v[214:217], v148 offset:38912
	ds_read_b128 v[218:221], v148 offset:39936
	global_load_lds_dwordx4 v[222:223], off
	v_lshl_add_u64 v[222:223], s[16:17], 0, v[134:135]
	s_mov_b32 m0, s58
	s_nop 0
	global_load_lds_dwordx4 v[222:223], off
	s_waitcnt lgkmcnt(8)
	s_barrier
	s_waitcnt lgkmcnt(0)
	s_setprio 1
	v_mfma_f32_16x16x32_bf16 v[124:127], v[140:143], v[190:193], v[124:127]
	v_mfma_f32_16x16x32_bf16 v[120:123], v[182:185], v[190:193], v[120:123]
	v_mfma_f32_16x16x32_bf16 v[108:111], v[140:143], v[198:201], v[108:111]
	v_mfma_f32_16x16x32_bf16 v[104:107], v[182:185], v[198:201], v[104:107]
	v_mfma_f32_16x16x32_bf16 v[92:95], v[140:143], v[206:209], v[92:95]
	v_mfma_f32_16x16x32_bf16 v[88:91], v[182:185], v[206:209], v[88:91]
	v_mfma_f32_16x16x32_bf16 v[76:79], v[140:143], v[214:217], v[76:79]
	v_mfma_f32_16x16x32_bf16 v[72:75], v[182:185], v[214:217], v[72:75]
	v_mfma_f32_16x16x32_bf16 v[124:127], v[178:181], v[194:197], v[124:127]
	v_mfma_f32_16x16x32_bf16 v[120:123], v[186:189], v[194:197], v[120:123]
	v_mfma_f32_16x16x32_bf16 v[108:111], v[178:181], v[202:205], v[108:111]
	v_mfma_f32_16x16x32_bf16 v[104:107], v[186:189], v[202:205], v[104:107]
	v_mfma_f32_16x16x32_bf16 v[92:95], v[178:181], v[210:213], v[92:95]
	v_mfma_f32_16x16x32_bf16 v[88:91], v[186:189], v[210:213], v[88:91]
	v_mfma_f32_16x16x32_bf16 v[76:79], v[178:181], v[218:221], v[76:79]
	v_mfma_f32_16x16x32_bf16 v[72:75], v[186:189], v[218:221], v[72:75]
	s_setprio 0
	s_barrier
	s_add_i32 s16, 0, 0x1c000
	s_add_i32 s17, s75, s65
	v_add_u32_e32 v128, s16, v146
	v_lshl_add_u64 v[144:145], v[144:145], 0, s[88:89]
	s_mov_b32 m0, s17
	ds_read_b128 v[222:225], v128
	ds_read_b128 v[226:229], v128 offset:1024
	ds_read_b128 v[230:233], v128 offset:2048
	ds_read_b128 v[234:237], v128 offset:3072
	global_load_lds_dwordx4 v[144:145], off
	v_lshl_add_u64 v[144:145], v[150:151], 0, s[88:89]
	s_add_i32 m0, s17, 0x2000
	s_nop 0
	global_load_lds_dwordx4 v[144:145], off
	s_barrier
	s_waitcnt lgkmcnt(0)
	s_setprio 1
	v_mfma_f32_16x16x32_bf16 v[116:119], v[222:225], v[190:193], v[116:119]
	v_mfma_f32_16x16x32_bf16 v[112:115], v[230:233], v[190:193], v[112:115]
	v_mfma_f32_16x16x32_bf16 v[100:103], v[222:225], v[198:201], v[100:103]
	v_mfma_f32_16x16x32_bf16 v[96:99], v[230:233], v[198:201], v[96:99]
	v_mfma_f32_16x16x32_bf16 v[84:87], v[222:225], v[206:209], v[84:87]
	v_mfma_f32_16x16x32_bf16 v[80:83], v[230:233], v[206:209], v[80:83]
	v_mfma_f32_16x16x32_bf16 v[68:71], v[222:225], v[214:217], v[68:71]
	v_mfma_f32_16x16x32_bf16 v[64:67], v[230:233], v[214:217], v[64:67]
	v_mfma_f32_16x16x32_bf16 v[116:119], v[226:229], v[194:197], v[116:119]
	v_mfma_f32_16x16x32_bf16 v[112:115], v[234:237], v[194:197], v[112:115]
	v_mfma_f32_16x16x32_bf16 v[100:103], v[226:229], v[202:205], v[100:103]
	v_mfma_f32_16x16x32_bf16 v[96:99], v[234:237], v[202:205], v[96:99]
	v_mfma_f32_16x16x32_bf16 v[84:87], v[226:229], v[210:213], v[84:87]
	v_mfma_f32_16x16x32_bf16 v[80:83], v[234:237], v[210:213], v[80:83]
	v_mfma_f32_16x16x32_bf16 v[68:71], v[226:229], v[218:221], v[68:71]
	v_mfma_f32_16x16x32_bf16 v[64:67], v[234:237], v[218:221], v[64:67]
	s_setprio 0
	s_mov_b32 m0, s82
	v_lshl_add_u64 v[144:145], v[162:163], 0, s[88:89]
	s_barrier
; DI unsigned pk2(float a, float b) { f32x2 v = {a, b}; nbf2 r = __builtin_convertvector(v, nbf2); return __builtin_bit_cast(unsigned, r); }
; #define PG8_STAGE(bufoff, gbase, voff) do { _Pragma("unroll") for (int _i = 0; _i < 2; ++_i) \
;         __builtin_amdgcn_global_load_lds((const unsigned*)((const char*)(gbase) + (voff)[_i]), (LAS unsigned*)(lds + (bufoff) + ldsw + _i * 8192), 16, 0, 0); } while (0)
; #define PG8_LDA(dst, b, h) do { _Pragma("unroll") for (int m = 0; m < 4; ++m) _Pragma("unroll") for (int k = 0; k < 2; ++k) dst[m][k] = *(const LAS bf16x8*)(lds + PG8_SA(b, h) + aoff + m * 2048 + k * 1024); } while (0)
; template <class Epi, class Sched>
; DI void gemm_phase(LAS unsigned char* lds, const Gemm g, const Sched& S, const Epi& E) {
;     ...
;             PG8_LDA(At, 1, 1); PG8_STAGE(PG8_SA(1, 0), a3, voffA);
;             PG8_BAR; PG8_WAIT_L(0); PG8_MMA(1, 0, At, B0); PG8_BAR; PG8_SCHED;
;             PG8_STAGE(PG8_SB(1, 1), b3 + hstep, voffB);
;             PG8_WAIT_V(6); PG8_BAR; PG8_MMA(1, 1, At, B1); PG8_BAR;
;         }
;         E(acc, cur, wr, wc, fr, fq);
;     DI void operator()(const f32x4 (&acc)[2][2][4][2], const pg8::Unit& u, int wr, int wc, int fr, int fq) const {
;         const int row0 = u.pm * 256 + wr * 64 + fr, colL = wc * 32 + 8 * fq;
;         const bool special = ((u.pm & 7) == 7 || u.pm == 64) && (u.pn < 6 || u.pn >= 8);
; #pragma unroll
;         for (int ai = 0; ai < 2; ++ai)
; #pragma unroll
;             for (int m = 0; m < 4; ++m) { const int r = row0 + ai * 128 + m * 16;
; #pragma unroll
;                 for (int bj = 0; bj < 2; ++bj) { const int pc = u.pn * 256 + bj * 128 + colL; const f32x4 v0 = acc[ai][bj][m][0], v1 = acc[ai][bj][m][1];
;                     u32x4 w; w.x = pk2(v0[0], v0[1]); w.y = pk2(v0[2], v0[3]); w.z = pk2(v1[0], v1[1]); w.w = pk2(v1[2], v1[3]);
;                     *(u32x4*)(P + (size_t)r * NPROJ + pc) = w;
;                     if (special) { float* dst = nullptr;
;                         if (r < NPROMPT) { const int tpos = r & 2047, b = r >> 11;
;                             if (pc < QKVD) { if (tpos >= 2045) dst = out + OUT_CP + ((size_t)(layer * 8 + b) * 3 + (tpos - 2045)) * QKVD + pc; }
;                             else if (pc >= 2048) { if (tpos >= 2033) dst = out + OUT_PP + ((size_t)(layer * 8 + b) * 15 + (tpos - 2033)) * 512 + (pc - 2048); } }
	ds_read_b128 v[190:193], v148 offset:49152
	ds_read_b128 v[194:197], v148 offset:50176
	ds_read_b128 v[198:201], v148 offset:51200
	ds_read_b128 v[202:205], v148 offset:52224
	ds_read_b128 v[206:209], v148 offset:53248
	ds_read_b128 v[210:213], v148 offset:54272
	ds_read_b128 v[214:217], v148 offset:55296
	ds_read_b128 v[218:221], v148 offset:56320
	global_load_lds_dwordx4 v[144:145], off
	v_lshl_add_u64 v[144:145], v[238:239], 0, s[88:89]
	s_mov_b32 m0, s83
	s_nop 0
	global_load_lds_dwordx4 v[144:145], off
	s_barrier
	s_waitcnt lgkmcnt(0)
	s_setprio 1
	v_mfma_f32_16x16x32_bf16 v[60:63], v[140:143], v[190:193], v[60:63]
	v_mfma_f32_16x16x32_bf16 v[56:59], v[182:185], v[190:193], v[56:59]
	v_mfma_f32_16x16x32_bf16 v[44:47], v[140:143], v[198:201], v[44:47]
	v_mfma_f32_16x16x32_bf16 v[40:43], v[182:185], v[198:201], v[40:43]
	v_mfma_f32_16x16x32_bf16 v[28:31], v[140:143], v[206:209], v[28:31]
	v_mfma_f32_16x16x32_bf16 v[24:27], v[182:185], v[206:209], v[24:27]
	v_mfma_f32_16x16x32_bf16 v[12:15], v[140:143], v[214:217], v[12:15]
	v_mfma_f32_16x16x32_bf16 v[8:11], v[182:185], v[214:217], v[8:11]
	v_mfma_f32_16x16x32_bf16 v[60:63], v[178:181], v[194:197], v[60:63]
	v_mfma_f32_16x16x32_bf16 v[56:59], v[186:189], v[194:197], v[56:59]
	v_mfma_f32_16x16x32_bf16 v[44:47], v[178:181], v[202:205], v[44:47]
	v_mfma_f32_16x16x32_bf16 v[40:43], v[186:189], v[202:205], v[40:43]
	v_mfma_f32_16x16x32_bf16 v[28:31], v[178:181], v[210:213], v[28:31]
	v_mfma_f32_16x16x32_bf16 v[24:27], v[186:189], v[210:213], v[24:27]
	v_mfma_f32_16x16x32_bf16 v[12:15], v[178:181], v[218:221], v[12:15]
	v_mfma_f32_16x16x32_bf16 v[8:11], v[186:189], v[218:221], v[8:11]
	s_setprio 0
	s_barrier
	s_add_u32 s14, s14, 0x40080
	s_addc_u32 s15, s15, 0
	s_add_i32 s16, s16, s65
	v_lshl_add_u64 v[140:141], s[14:15], 0, v[132:133]
	s_mov_b32 m0, s16
	s_nop 0
	global_load_lds_dwordx4 v[140:141], off
	v_lshl_add_u64 v[140:141], s[14:15], 0, v[134:135]
	s_add_i32 m0, s16, 0x2000
	s_nop 0
	global_load_lds_dwordx4 v[140:141], off
	s_waitcnt vmcnt(6)
	s_barrier
	s_setprio 1
	v_mfma_f32_16x16x32_bf16 v[52:55], v[222:225], v[190:193], v[52:55]
	v_mfma_f32_16x16x32_bf16 v[48:51], v[230:233], v[190:193], v[48:51]
	v_mfma_f32_16x16x32_bf16 v[36:39], v[222:225], v[198:201], v[36:39]
	v_mfma_f32_16x16x32_bf16 v[32:35], v[230:233], v[198:201], v[32:35]
	v_mfma_f32_16x16x32_bf16 v[20:23], v[222:225], v[206:209], v[20:23]
	v_mfma_f32_16x16x32_bf16 v[16:19], v[230:233], v[206:209], v[16:19]
	v_mfma_f32_16x16x32_bf16 v[4:7], v[222:225], v[214:217], v[4:7]
	v_mfma_f32_16x16x32_bf16 v[0:3], v[230:233], v[214:217], v[0:3]
	v_mfma_f32_16x16x32_bf16 v[52:55], v[226:229], v[194:197], v[52:55]
	v_mfma_f32_16x16x32_bf16 v[48:51], v[234:237], v[194:197], v[48:51]
	v_mfma_f32_16x16x32_bf16 v[36:39], v[226:229], v[202:205], v[36:39]
	v_mfma_f32_16x16x32_bf16 v[32:35], v[234:237], v[202:205], v[32:35]
	v_mfma_f32_16x16x32_bf16 v[20:23], v[226:229], v[210:213], v[20:23]
	v_mfma_f32_16x16x32_bf16 v[16:19], v[234:237], v[210:213], v[16:19]
	v_mfma_f32_16x16x32_bf16 v[4:7], v[226:229], v[218:221], v[4:7]
	v_mfma_f32_16x16x32_bf16 v[0:3], v[234:237], v[218:221], v[0:3]
	s_setprio 0
	s_add_i32 s41, s41, 2
	s_add_u32 s8, s8, 0x100
	s_addc_u32 s9, s9, 0
	s_add_u32 s39, s39, 0x100
	s_addc_u32 s40, s40, 0
	s_cmp_gt_u32 s41, 13
	s_barrier
	s_cbranch_scc0 .LBB0_503
	s_lshl_b32 s75, s12, 8
	s_add_i32 s75, s75, s91
	s_and_b32 s8, s12, 7
	s_cmp_eq_u32 s8, 7
	s_cselect_b64 s[8:9], -1, 0
	s_cmp_eq_u32 s12, 64
	s_cselect_b64 s[12:13], -1, 0
	s_or_b64 s[8:9], s[12:13], s[8:9]
	s_add_i32 s11, s10, -8
	s_cmp_lt_u32 s11, -2
	s_cselect_b64 s[12:13], -1, 0
	s_lshl_b32 s35, s10, 8
	v_or_b32_e32 v149, s75, v131
	s_and_b64 s[14:15], s[8:9], s[12:13]
	v_or_b32_e32 v140, s35, v147
	v_mov_b64_e32 v[142:143], s[72:73]
	s_cmpk_gt_u32 s75, 0x407f
	v_mad_i64_i32 v[142:143], s[8:9], v149, s42, v[142:143]
	v_ashrrev_i32_e32 v141, 31, v140
	v_cndmask_b32_e64 v144, 0, 1, s[14:15]
	v_cmp_gt_i32_e64 s[10:11], s45, v149
	s_cselect_b64 s[12:13], -1, 0
	v_add_u32_e32 v128, 0xffffc000, v149
	v_cvt_pk_bf16_f32 v178, v124, v125
	v_cvt_pk_bf16_f32 v179, v126, v127
	v_cvt_pk_bf16_f32 v180, v120, v121
	v_cvt_pk_bf16_f32 v181, v122, v123
	v_lshl_add_u64 v[142:143], v[140:141], 1, v[142:143]
	v_cmp_ne_u32_e64 s[8:9], 1, v144
	s_andn2_b64 vcc, exec, s[14:15]
	global_store_dwordx4 v[142:143], v[178:181], off
	s_cbranch_vccnz .LBB0_515
	s_nor_b64 s[16:17], s[12:13], s[10:11]
	v_mov_b64_e32 v[144:145], 0
	s_and_saveexec_b64 s[14:15], s[16:17]
	s_cbranch_execz .LBB0_512
	v_cmp_lt_i32_e32 vcc, s55, v140
	s_and_saveexec_b64 s[16:17], vcc
	s_xor_b64 s[16:17], exec, s[16:17]
	s_cbranch_execz .LBB0_509
	s_cmpk_lt_u32 s35, 0x800
	v_mov_b64_e32 v[144:145], 0
	s_cbranch_scc1 .LBB0_509
	v_add_u32_e32 v150, s78, v128
	v_mov_b64_e32 v[144:145], s[20:21]
	s_movk_i32 s38, 0x7800
	v_mad_i64_i32 v[144:145], s[38:39], v150, s38, v[144:145]
	v_lshl_add_u64 v[144:145], v[140:141], 2, v[144:145]
	s_mov_b64 s[38:39], 0xd305000
	v_lshl_add_u64 v[144:145], v[144:145], 0, s[38:39]

; #define PG8_STAGE(bufoff, gbase, voff) do { _Pragma("unroll") for (int _i = 0; _i < 2; ++_i) \
;         __builtin_amdgcn_global_load_lds((const unsigned*)((const char*)(gbase) + (voff)[_i]), (LAS unsigned*)(lds + (bufoff) + ldsw + _i * 8192), 16, 0, 0); } while (0)
; #define PG8_LDA(dst, b, h) do { _Pragma("unroll") for (int m = 0; m < 4; ++m) _Pragma("unroll") for (int k = 0; k < 2; ++k) dst[m][k] = *(const LAS bf16x8*)(lds + PG8_SA(b, h) + aoff + m * 2048 + k * 1024); } while (0)
; #define PG8_LDB(dst, b, h) do { _Pragma("unroll") for (int n = 0; n < 2; ++n) _Pragma("unroll") for (int k = 0; k < 2; ++k) dst[n][k] = *(const LAS bf16x8*)(lds + PG8_SB(b, h) + boff + n * 2048 + k * 1024); } while (0)
; #define PG8_MMA(ai, bj, At, Bt) do { __builtin_amdgcn_s_setprio(1); _Pragma("unroll") for (int m = 0; m < 4; ++m) _Pragma("unroll") for (int n = 0; n < 2; ++n) _Pragma("unroll") for (int k = 0; k < 2; ++k) \
;         acc[ai][bj][m][n] = __builtin_amdgcn_mfma_f32_16x16x32_bf16(Bt[n][k], At[m][k], acc[ai][bj][m][n], 0, 0, 0); __builtin_amdgcn_s_setprio(0); } while (0)
; #define PG8_WAIT_L(n) asm volatile("s_waitcnt lgkmcnt(" #n ")" ::: "memory")
; #define PG8_BAR __builtin_amdgcn_s_barrier()
; #define PG8_SCHED __builtin_amdgcn_sched_barrier(0)
; template <class Epi, class Sched>
; DI void gemm_phase(LAS unsigned char* lds, const Gemm g, const Sched& S, const Epi& E) {
;     ...
;             PG8_LDB(B0, 0, 0); PG8_SCHED; PG8_LDA(At, 0, 0); PG8_STAGE(PG8_SA(1, 1), a1 + hstep, voffA);
;             PG8_WAIT_L(8); PG8_BAR; PG8_WAIT_L(0); PG8_MMA(0, 0, At, B0); PG8_BAR; PG8_SCHED;
;             PG8_LDB(B1, 0, 1); PG8_STAGE(PG8_SB(0, 0), b2, voffB);
;             PG8_BAR; PG8_WAIT_L(0); PG8_MMA(0, 1, At, B1); PG8_BAR;
;             PG8_LDA(At, 0, 1); PG8_STAGE(PG8_SA(0, 0), a2, voffA);
;             PG8_BAR; PG8_WAIT_L(0); PG8_MMA(1, 0, At, B0); PG8_BAR; PG8_SCHED;
.LBB0_800:
	s_add_u32 s34, s18, s28
	s_addc_u32 s35, s19, s29
	s_add_u32 s34, s34, 0x100
	s_addc_u32 s35, s35, 0
	s_add_u32 s36, s13, s28
	s_addc_u32 s37, s95, s29
	s_add_i32 s92, 0, 0x10000
	v_add_u32_e32 v150, s92, v131
	ds_read_b128 v[180:183], v150
	ds_read_b128 v[184:187], v150 offset:1024
	ds_read_b128 v[188:191], v150 offset:2048
	ds_read_b128 v[192:195], v150 offset:3072
	s_cmp_eq_u32 s17, vcc_lo
	s_cselect_b32 s35, s15, s35
	s_cselect_b32 s34, s14, s34
	s_cselect_b32 s37, s9, s37
	s_cselect_b32 s36, s8, s36
	v_lshl_add_u64 v[150:151], v[146:147], 0, s[28:29]
	s_add_i32 m0, s67, 0xc000
	ds_read_b128 v[196:199], v178
	ds_read_b128 v[200:203], v178 offset:1024
	ds_read_b128 v[204:207], v178 offset:2048
	ds_read_b128 v[208:211], v178 offset:3072
	ds_read_b128 v[212:215], v178 offset:4096
	ds_read_b128 v[216:219], v178 offset:5120
	ds_read_b128 v[220:223], v178 offset:6144
	ds_read_b128 v[224:227], v178 offset:7168
	global_load_lds_dwordx4 v[150:151], off
	v_lshl_add_u64 v[150:151], v[148:149], 0, s[28:29]
	s_add_i32 m0, s67, 0xe000
	s_nop 0
	global_load_lds_dwordx4 v[150:151], off
	s_waitcnt lgkmcnt(8)
	s_barrier
	s_waitcnt lgkmcnt(0)
	s_setprio 1
	v_mfma_f32_16x16x32_bf16 v[124:127], v[180:183], v[196:199], v[124:127]
	v_mfma_f32_16x16x32_bf16 v[120:123], v[188:191], v[196:199], v[120:123]
	v_mfma_f32_16x16x32_bf16 v[112:115], v[180:183], v[204:207], v[112:115]
	v_mfma_f32_16x16x32_bf16 v[104:107], v[188:191], v[204:207], v[104:107]
	v_mfma_f32_16x16x32_bf16 v[96:99], v[180:183], v[212:215], v[96:99]
	v_mfma_f32_16x16x32_bf16 v[88:91], v[188:191], v[212:215], v[88:91]
	v_mfma_f32_16x16x32_bf16 v[80:83], v[180:183], v[220:223], v[80:83]
	v_mfma_f32_16x16x32_bf16 v[72:75], v[188:191], v[220:223], v[72:75]
	v_mfma_f32_16x16x32_bf16 v[124:127], v[184:187], v[200:203], v[124:127]
	v_mfma_f32_16x16x32_bf16 v[120:123], v[192:195], v[200:203], v[120:123]
	v_mfma_f32_16x16x32_bf16 v[112:115], v[184:187], v[208:211], v[112:115]
	v_mfma_f32_16x16x32_bf16 v[104:107], v[192:195], v[208:211], v[104:107]
	v_mfma_f32_16x16x32_bf16 v[96:99], v[184:187], v[216:219], v[96:99]
	v_mfma_f32_16x16x32_bf16 v[88:91], v[192:195], v[216:219], v[88:91]
	v_mfma_f32_16x16x32_bf16 v[80:83], v[184:187], v[224:227], v[80:83]
	v_mfma_f32_16x16x32_bf16 v[72:75], v[192:195], v[224:227], v[72:75]
	s_setprio 0
	s_barrier
	s_add_i32 s93, 0, 0x14000
	v_add_u32_e32 v150, s93, v131
	s_add_i32 s92, s92, s66
	ds_read_b128 v[228:231], v150
	ds_read_b128 v[232:235], v150 offset:1024
	ds_read_b128 v[236:239], v150 offset:2048
	ds_read_b128 v[240:243], v150 offset:3072
	v_lshl_add_u64 v[150:151], s[36:37], 0, v[128:129]
	s_mov_b32 m0, s92
	v_lshl_add_u64 v[244:245], s[36:37], 0, v[132:133]
	global_load_lds_dwordx4 v[150:151], off
	s_add_i32 m0, s92, 0x2000
	s_nop 0
	global_load_lds_dwordx4 v[244:245], off
	s_barrier
	s_waitcnt lgkmcnt(0)
	s_setprio 1
	v_mfma_f32_16x16x32_bf16 v[116:119], v[228:231], v[196:199], v[116:119]
	v_mfma_f32_16x16x32_bf16 v[108:111], v[236:239], v[196:199], v[108:111]
	v_mfma_f32_16x16x32_bf16 v[100:103], v[228:231], v[204:207], v[100:103]
	v_mfma_f32_16x16x32_bf16 v[92:95], v[236:239], v[204:207], v[92:95]
	v_mfma_f32_16x16x32_bf16 v[84:87], v[228:231], v[212:215], v[84:87]
	v_mfma_f32_16x16x32_bf16 v[76:79], v[236:239], v[212:215], v[76:79]
	v_mfma_f32_16x16x32_bf16 v[68:71], v[228:231], v[220:223], v[68:71]
	v_mfma_f32_16x16x32_bf16 v[64:67], v[236:239], v[220:223], v[64:67]
	v_mfma_f32_16x16x32_bf16 v[116:119], v[232:235], v[200:203], v[116:119]
	v_mfma_f32_16x16x32_bf16 v[108:111], v[240:243], v[200:203], v[108:111]
	v_mfma_f32_16x16x32_bf16 v[100:103], v[232:235], v[208:211], v[100:103]
	v_mfma_f32_16x16x32_bf16 v[92:95], v[240:243], v[208:211], v[92:95]
	v_mfma_f32_16x16x32_bf16 v[84:87], v[232:235], v[216:219], v[84:87]
	v_mfma_f32_16x16x32_bf16 v[76:79], v[240:243], v[216:219], v[76:79]
	v_mfma_f32_16x16x32_bf16 v[68:71], v[232:235], v[224:227], v[68:71]
	v_mfma_f32_16x16x32_bf16 v[64:67], v[240:243], v[224:227], v[64:67]
	s_setprio 0
	s_mov_b32 m0, s67
	v_lshl_add_u64 v[246:247], s[34:35], 0, v[128:129]
	s_barrier
	ds_read_b128 v[196:199], v178 offset:16384
	ds_read_b128 v[200:203], v178 offset:17408
	ds_read_b128 v[204:207], v178 offset:18432
	ds_read_b128 v[208:211], v178 offset:19456
	ds_read_b128 v[212:215], v178 offset:20480
	ds_read_b128 v[216:219], v178 offset:21504
	ds_read_b128 v[220:223], v178 offset:22528
	ds_read_b128 v[224:227], v178 offset:23552
	global_load_lds_dwordx4 v[246:247], off
	v_lshl_add_u64 v[248:249], s[34:35], 0, v[132:133]
	s_mov_b32 m0, s77
	s_nop 0
	global_load_lds_dwordx4 v[248:249], off
	s_barrier
	s_waitcnt lgkmcnt(0)
	s_setprio 1
	v_mfma_f32_16x16x32_bf16 v[60:63], v[180:183], v[196:199], v[60:63]
	v_mfma_f32_16x16x32_bf16 v[56:59], v[188:191], v[196:199], v[56:59]
	v_mfma_f32_16x16x32_bf16 v[48:51], v[180:183], v[204:207], v[48:51]
	v_mfma_f32_16x16x32_bf16 v[40:43], v[188:191], v[204:207], v[40:43]
	v_mfma_f32_16x16x32_bf16 v[32:35], v[180:183], v[212:215], v[32:35]
	v_mfma_f32_16x16x32_bf16 v[24:27], v[188:191], v[212:215], v[24:27]
	v_mfma_f32_16x16x32_bf16 v[16:19], v[180:183], v[220:223], v[16:19]
	v_mfma_f32_16x16x32_bf16 v[8:11], v[188:191], v[220:223], v[8:11]
	v_mfma_f32_16x16x32_bf16 v[60:63], v[184:187], v[200:203], v[60:63]
	v_mfma_f32_16x16x32_bf16 v[56:59], v[192:195], v[200:203], v[56:59]
	v_mfma_f32_16x16x32_bf16 v[48:51], v[184:187], v[208:211], v[48:51]
	v_mfma_f32_16x16x32_bf16 v[40:43], v[192:195], v[208:211], v[40:43]
	v_mfma_f32_16x16x32_bf16 v[32:35], v[184:187], v[216:219], v[32:35]
	v_mfma_f32_16x16x32_bf16 v[24:27], v[192:195], v[216:219], v[24:27]
	v_mfma_f32_16x16x32_bf16 v[16:19], v[184:187], v[224:227], v[16:19]
	v_mfma_f32_16x16x32_bf16 v[8:11], v[192:195], v[224:227], v[8:11]
	s_setprio 0
	s_barrier
; #define PG8_STAGE(bufoff, gbase, voff) do { _Pragma("unroll") for (int _i = 0; _i < 2; ++_i) \
;         __builtin_amdgcn_global_load_lds((const unsigned*)((const char*)(gbase) + (voff)[_i]), (LAS unsigned*)(lds + (bufoff) + ldsw + _i * 8192), 16, 0, 0); } while (0)
; #define PG8_LDA(dst, b, h) do { _Pragma("unroll") for (int m = 0; m < 4; ++m) _Pragma("unroll") for (int k = 0; k < 2; ++k) dst[m][k] = *(const LAS bf16x8*)(lds + PG8_SA(b, h) + aoff + m * 2048 + k * 1024); } while (0)
; #define PG8_LDB(dst, b, h) do { _Pragma("unroll") for (int n = 0; n < 2; ++n) _Pragma("unroll") for (int k = 0; k < 2; ++k) dst[n][k] = *(const LAS bf16x8*)(lds + PG8_SB(b, h) + boff + n * 2048 + k * 1024); } while (0)
; #define PG8_MMA(ai, bj, At, Bt) do { __builtin_amdgcn_s_setprio(1); _Pragma("unroll") for (int m = 0; m < 4; ++m) _Pragma("unroll") for (int n = 0; n < 2; ++n) _Pragma("unroll") for (int k = 0; k < 2; ++k) \
;         acc[ai][bj][m][n] = __builtin_amdgcn_mfma_f32_16x16x32_bf16(Bt[n][k], At[m][k], acc[ai][bj][m][n], 0, 0, 0); __builtin_amdgcn_s_setprio(0); } while (0)
; #define PG8_WAIT_V(n) asm volatile("s_waitcnt vmcnt(" #n ")" ::: "memory")
; #define PG8_WAIT_L(n) asm volatile("s_waitcnt lgkmcnt(" #n ")" ::: "memory")
; #define PG8_BAR __builtin_amdgcn_s_barrier()
; #define PG8_SCHED __builtin_amdgcn_sched_barrier(0)
; template <class Epi, class Sched>
; DI void gemm_phase(LAS unsigned char* lds, const Gemm g, const Sched& S, const Epi& E) {
;     ...
;             PG8_STAGE(PG8_SB(0, 1), b2 + hstep, voffB);
;             PG8_WAIT_V(6); PG8_BAR; PG8_MMA(1, 1, At, B1); PG8_BAR;
;             PG8_LDB(B0, 1, 0); PG8_SCHED; PG8_LDA(At, 1, 0); PG8_STAGE(PG8_SA(0, 1), a2 + hstep, voffA);
;             PG8_WAIT_L(8); PG8_BAR; PG8_WAIT_L(0); PG8_MMA(0, 0, At, B0); PG8_BAR; PG8_SCHED;
;             PG8_LDB(B1, 1, 1); PG8_STAGE(PG8_SB(1, 0), b3, voffB);
;             PG8_BAR; PG8_WAIT_L(0); PG8_MMA(0, 1, At, B1); PG8_BAR;
;             PG8_LDA(At, 1, 1); PG8_STAGE(PG8_SA(1, 0), a3, voffA);
;             PG8_BAR; PG8_WAIT_L(0); PG8_MMA(1, 0, At, B0); PG8_BAR; PG8_SCHED;
	s_add_u32 s36, s36, s2
	s_addc_u32 s37, s37, 0
	s_add_i32 s92, s93, s66
	v_lshl_add_u64 v[250:251], s[36:37], 0, v[128:129]
	s_mov_b32 m0, s92
	v_lshl_add_u64 v[162:163], s[36:37], 0, v[132:133]
	global_load_lds_dwordx4 v[250:251], off
	s_add_i32 m0, s92, 0x2000
	s_nop 0
	global_load_lds_dwordx4 v[162:163], off
	s_waitcnt vmcnt(6)
	s_barrier
	s_setprio 1
	v_mfma_f32_16x16x32_bf16 v[52:55], v[228:231], v[196:199], v[52:55]
	v_mfma_f32_16x16x32_bf16 v[44:47], v[236:239], v[196:199], v[44:47]
	v_mfma_f32_16x16x32_bf16 v[36:39], v[228:231], v[204:207], v[36:39]
	v_mfma_f32_16x16x32_bf16 v[28:31], v[236:239], v[204:207], v[28:31]
	v_mfma_f32_16x16x32_bf16 v[20:23], v[228:231], v[212:215], v[20:23]
	v_mfma_f32_16x16x32_bf16 v[12:15], v[236:239], v[212:215], v[12:15]
	v_mfma_f32_16x16x32_bf16 v[4:7], v[228:231], v[220:223], v[4:7]
	v_mfma_f32_16x16x32_bf16 v[0:3], v[236:239], v[220:223], v[0:3]
	v_mfma_f32_16x16x32_bf16 v[52:55], v[232:235], v[200:203], v[52:55]
	v_mfma_f32_16x16x32_bf16 v[44:47], v[240:243], v[200:203], v[44:47]
	v_mfma_f32_16x16x32_bf16 v[36:39], v[232:235], v[208:211], v[36:39]
	v_mfma_f32_16x16x32_bf16 v[28:31], v[240:243], v[208:211], v[28:31]
	v_mfma_f32_16x16x32_bf16 v[20:23], v[232:235], v[216:219], v[20:23]
	v_mfma_f32_16x16x32_bf16 v[12:15], v[240:243], v[216:219], v[12:15]
	v_mfma_f32_16x16x32_bf16 v[4:7], v[232:235], v[224:227], v[4:7]
	v_mfma_f32_16x16x32_bf16 v[0:3], v[240:243], v[224:227], v[0:3]
	s_setprio 0
	s_add_i32 s36, 0, 0x18000
	v_add_u32_e32 v192, s36, v131
	s_barrier
	ds_read_b128 v[180:183], v192
	ds_read_b128 v[184:187], v192 offset:1024
	ds_read_b128 v[188:191], v192 offset:2048
	ds_read_b128 v[192:195], v192 offset:3072
	s_add_u32 s34, s34, s2
	s_addc_u32 s35, s35, 0
	s_mov_b32 m0, s78
	v_lshl_add_u64 v[228:229], s[34:35], 0, v[128:129]
	ds_read_b128 v[196:199], v178 offset:32768
	ds_read_b128 v[200:203], v178 offset:33792
	ds_read_b128 v[204:207], v178 offset:34816
	ds_read_b128 v[208:211], v178 offset:35840
	ds_read_b128 v[212:215], v178 offset:36864
	ds_read_b128 v[216:219], v178 offset:37888
	ds_read_b128 v[220:223], v178 offset:38912
	ds_read_b128 v[224:227], v178 offset:39936
	global_load_lds_dwordx4 v[228:229], off
	v_lshl_add_u64 v[228:229], s[34:35], 0, v[132:133]
	s_mov_b32 m0, s79
	s_nop 0
	global_load_lds_dwordx4 v[228:229], off
	s_waitcnt lgkmcnt(8)
	s_barrier
	s_waitcnt lgkmcnt(0)
	s_setprio 1
	v_mfma_f32_16x16x32_bf16 v[124:127], v[180:183], v[196:199], v[124:127]
	v_mfma_f32_16x16x32_bf16 v[120:123], v[188:191], v[196:199], v[120:123]
	v_mfma_f32_16x16x32_bf16 v[112:115], v[180:183], v[204:207], v[112:115]
	v_mfma_f32_16x16x32_bf16 v[104:107], v[188:191], v[204:207], v[104:107]
	v_mfma_f32_16x16x32_bf16 v[96:99], v[180:183], v[212:215], v[96:99]
	v_mfma_f32_16x16x32_bf16 v[88:91], v[188:191], v[212:215], v[88:91]
	v_mfma_f32_16x16x32_bf16 v[80:83], v[180:183], v[220:223], v[80:83]
	v_mfma_f32_16x16x32_bf16 v[72:75], v[188:191], v[220:223], v[72:75]
	v_mfma_f32_16x16x32_bf16 v[124:127], v[184:187], v[200:203], v[124:127]
	v_mfma_f32_16x16x32_bf16 v[120:123], v[192:195], v[200:203], v[120:123]
	v_mfma_f32_16x16x32_bf16 v[112:115], v[184:187], v[208:211], v[112:115]
	v_mfma_f32_16x16x32_bf16 v[104:107], v[192:195], v[208:211], v[104:107]
	v_mfma_f32_16x16x32_bf16 v[96:99], v[184:187], v[216:219], v[96:99]
	v_mfma_f32_16x16x32_bf16 v[88:91], v[192:195], v[216:219], v[88:91]
	v_mfma_f32_16x16x32_bf16 v[80:83], v[184:187], v[224:227], v[80:83]
	v_mfma_f32_16x16x32_bf16 v[72:75], v[192:195], v[224:227], v[72:75]
	s_setprio 0
	s_barrier
	s_add_i32 s34, 0, 0x1c000
	s_add_i32 s35, s36, s66
	v_add_u32_e32 v240, s34, v131
	v_lshl_add_u64 v[150:151], v[150:151], 0, s[88:89]
	s_mov_b32 m0, s35
	ds_read_b128 v[228:231], v240
	ds_read_b128 v[232:235], v240 offset:1024
	ds_read_b128 v[236:239], v240 offset:2048
	ds_read_b128 v[240:243], v240 offset:3072
	global_load_lds_dwordx4 v[150:151], off
	v_lshl_add_u64 v[150:151], v[244:245], 0, s[88:89]
	s_add_i32 m0, s35, 0x2000
	s_nop 0
	global_load_lds_dwordx4 v[150:151], off
	s_barrier
	s_waitcnt lgkmcnt(0)
	s_setprio 1
	v_mfma_f32_16x16x32_bf16 v[116:119], v[228:231], v[196:199], v[116:119]
	v_mfma_f32_16x16x32_bf16 v[108:111], v[236:239], v[196:199], v[108:111]
	v_mfma_f32_16x16x32_bf16 v[100:103], v[228:231], v[204:207], v[100:103]
	v_mfma_f32_16x16x32_bf16 v[92:95], v[236:239], v[204:207], v[92:95]
	v_mfma_f32_16x16x32_bf16 v[84:87], v[228:231], v[212:215], v[84:87]
	v_mfma_f32_16x16x32_bf16 v[76:79], v[236:239], v[212:215], v[76:79]
	v_mfma_f32_16x16x32_bf16 v[68:71], v[228:231], v[220:223], v[68:71]
	v_mfma_f32_16x16x32_bf16 v[64:67], v[236:239], v[220:223], v[64:67]
	v_mfma_f32_16x16x32_bf16 v[116:119], v[232:235], v[200:203], v[116:119]
	v_mfma_f32_16x16x32_bf16 v[108:111], v[240:243], v[200:203], v[108:111]
	v_mfma_f32_16x16x32_bf16 v[100:103], v[232:235], v[208:211], v[100:103]
	v_mfma_f32_16x16x32_bf16 v[92:95], v[240:243], v[208:211], v[92:95]
	v_mfma_f32_16x16x32_bf16 v[84:87], v[232:235], v[216:219], v[84:87]
	v_mfma_f32_16x16x32_bf16 v[76:79], v[240:243], v[216:219], v[76:79]
	v_mfma_f32_16x16x32_bf16 v[68:71], v[232:235], v[224:227], v[68:71]
	v_mfma_f32_16x16x32_bf16 v[64:67], v[240:243], v[224:227], v[64:67]
	s_setprio 0
	s_mov_b32 m0, s80
	v_lshl_add_u64 v[150:151], v[246:247], 0, s[88:89]
	s_barrier
	ds_read_b128 v[196:199], v178 offset:49152
	ds_read_b128 v[200:203], v178 offset:50176
	ds_read_b128 v[204:207], v178 offset:51200
	ds_read_b128 v[208:211], v178 offset:52224
	ds_read_b128 v[212:215], v178 offset:53248
	ds_read_b128 v[216:219], v178 offset:54272
	ds_read_b128 v[220:223], v178 offset:55296
	ds_read_b128 v[224:227], v178 offset:56320
	global_load_lds_dwordx4 v[150:151], off
	v_lshl_add_u64 v[150:151], v[248:249], 0, s[88:89]
	s_mov_b32 m0, s81
	s_nop 0
	global_load_lds_dwordx4 v[150:151], off
	s_barrier
; #define PG8_STAGE(bufoff, gbase, voff) do { _Pragma("unroll") for (int _i = 0; _i < 2; ++_i) \
;         __builtin_amdgcn_global_load_lds((const unsigned*)((const char*)(gbase) + (voff)[_i]), (LAS unsigned*)(lds + (bufoff) + ldsw + _i * 8192), 16, 0, 0); } while (0)
; #define PG8_MMA(ai, bj, At, Bt) do { __builtin_amdgcn_s_setprio(1); _Pragma("unroll") for (int m = 0; m < 4; ++m) _Pragma("unroll") for (int n = 0; n < 2; ++n) _Pragma("unroll") for (int k = 0; k < 2; ++k) \
;         acc[ai][bj][m][n] = __builtin_amdgcn_mfma_f32_16x16x32_bf16(Bt[n][k], At[m][k], acc[ai][bj][m][n], 0, 0, 0); __builtin_amdgcn_s_setprio(0); } while (0)
; #define PG8_WAIT_V(n) asm volatile("s_waitcnt vmcnt(" #n ")" ::: "memory")
; #define PG8_WAIT_L(n) asm volatile("s_waitcnt lgkmcnt(" #n ")" ::: "memory")
; #define PG8_BAR __builtin_amdgcn_s_barrier()
; #define PG8_SCHED __builtin_amdgcn_sched_barrier(0)
; template <class Epi, class Sched>
; DI void gemm_phase(LAS unsigned char* lds, const Gemm g, const Sched& S, const Epi& E) {
;     ...
;             PG8_BAR; PG8_WAIT_L(0); PG8_MMA(1, 0, At, B0); PG8_BAR; PG8_SCHED;
;             PG8_STAGE(PG8_SB(1, 1), b3 + hstep, voffB);
;             PG8_WAIT_V(6); PG8_BAR; PG8_MMA(1, 1, At, B1); PG8_BAR;
;         }
;         E(acc, cur, wr, wc, fr, fq);
	s_waitcnt lgkmcnt(0)
	s_setprio 1
	v_mfma_f32_16x16x32_bf16 v[60:63], v[180:183], v[196:199], v[60:63]
	v_mfma_f32_16x16x32_bf16 v[56:59], v[188:191], v[196:199], v[56:59]
	v_mfma_f32_16x16x32_bf16 v[48:51], v[180:183], v[204:207], v[48:51]
	v_mfma_f32_16x16x32_bf16 v[40:43], v[188:191], v[204:207], v[40:43]
	v_mfma_f32_16x16x32_bf16 v[32:35], v[180:183], v[212:215], v[32:35]
	v_mfma_f32_16x16x32_bf16 v[24:27], v[188:191], v[212:215], v[24:27]
	v_mfma_f32_16x16x32_bf16 v[16:19], v[180:183], v[220:223], v[16:19]
	v_mfma_f32_16x16x32_bf16 v[8:11], v[188:191], v[220:223], v[8:11]
	v_mfma_f32_16x16x32_bf16 v[60:63], v[184:187], v[200:203], v[60:63]
	v_mfma_f32_16x16x32_bf16 v[56:59], v[192:195], v[200:203], v[56:59]
	v_mfma_f32_16x16x32_bf16 v[48:51], v[184:187], v[208:211], v[48:51]
	v_mfma_f32_16x16x32_bf16 v[40:43], v[192:195], v[208:211], v[40:43]
	v_mfma_f32_16x16x32_bf16 v[32:35], v[184:187], v[216:219], v[32:35]
	v_mfma_f32_16x16x32_bf16 v[24:27], v[192:195], v[216:219], v[24:27]
	v_mfma_f32_16x16x32_bf16 v[16:19], v[184:187], v[224:227], v[16:19]
	v_mfma_f32_16x16x32_bf16 v[8:11], v[192:195], v[224:227], v[8:11]
	s_setprio 0
	s_barrier
	s_add_i32 s34, s34, s66
	v_lshl_add_u64 v[150:151], v[250:251], 0, s[88:89]
	s_mov_b32 m0, s34
	s_nop 0
	global_load_lds_dwordx4 v[150:151], off
	v_lshl_add_u64 v[150:151], v[162:163], 0, s[88:89]
	s_add_i32 m0, s34, 0x2000
	s_nop 0
	global_load_lds_dwordx4 v[150:151], off
	s_waitcnt vmcnt(6)
	s_barrier
	s_setprio 1
	v_mfma_f32_16x16x32_bf16 v[52:55], v[228:231], v[196:199], v[52:55]
	v_mfma_f32_16x16x32_bf16 v[44:47], v[236:239], v[196:199], v[44:47]
	v_mfma_f32_16x16x32_bf16 v[36:39], v[228:231], v[204:207], v[36:39]
	v_mfma_f32_16x16x32_bf16 v[28:31], v[236:239], v[204:207], v[28:31]
	v_mfma_f32_16x16x32_bf16 v[20:23], v[228:231], v[212:215], v[20:23]
	v_mfma_f32_16x16x32_bf16 v[12:15], v[236:239], v[212:215], v[12:15]
	v_mfma_f32_16x16x32_bf16 v[4:7], v[228:231], v[220:223], v[4:7]
	v_mfma_f32_16x16x32_bf16 v[0:3], v[236:239], v[220:223], v[0:3]
	v_mfma_f32_16x16x32_bf16 v[52:55], v[232:235], v[200:203], v[52:55]
	v_mfma_f32_16x16x32_bf16 v[44:47], v[240:243], v[200:203], v[44:47]
	v_mfma_f32_16x16x32_bf16 v[36:39], v[232:235], v[208:211], v[36:39]
	v_mfma_f32_16x16x32_bf16 v[28:31], v[240:243], v[208:211], v[28:31]
	v_mfma_f32_16x16x32_bf16 v[20:23], v[232:235], v[216:219], v[20:23]
	v_mfma_f32_16x16x32_bf16 v[12:15], v[240:243], v[216:219], v[12:15]
	v_mfma_f32_16x16x32_bf16 v[4:7], v[232:235], v[224:227], v[4:7]
	v_mfma_f32_16x16x32_bf16 v[0:3], v[240:243], v[224:227], v[0:3]
	s_setprio 0
	s_add_i32 s34, vcc_lo, 2
	s_add_u32 s28, s28, 0x100
	s_addc_u32 s29, s29, 0
	s_cmp_ge_i32 vcc_lo, s17
	s_mov_b32 vcc_lo, s34
	s_barrier
	s_cbranch_scc0 .LBB0_800
	v_lshl_or_b32 v146, s94, 8, v137
	v_cmp_ne_u32_e32 vcc, 0, v135
	v_ashrrev_i32_e32 v147, 31, v146
	s_cbranch_vccz .LBB0_803
;     DI void operator()(const f32x4 (&acc)[2][2][4][2], const pg8::Unit& u, int wr, int wc, int fr, int fq) const {
;     ...
;         if (u.split) {
;             float* P0 = PART + ((size_t)(u.kt0 / u.nt) * 256 + (wr * 64 + fr)) * DM + col0;
; #pragma unroll
;             for (int ai = 0; ai < 2; ++ai)
; #pragma unroll
;                 for (int m = 0; m < 4; ++m) { float* rowp = P0 + (size_t)(ai * 128 + m * 16) * DM;
; #pragma unroll
;                     for (int bj = 0; bj < 2; ++bj)
; #pragma unroll
;                         for (int n = 0; n < 2; ++n) *(f32x4*)(rowp + bj * 128 + n * 16) = acc[ai][bj][m][n] * scale; }
;             return; }
	s_abs_i32 s13, s17
	v_cvt_f32_u32_e32 v135, s13
	s_sub_i32 s18, 0, s13
	s_xor_b32 s17, s16, s17
	s_abs_i32 s16, s16
	v_rcp_iflag_f32_e32 v148, v135
	s_ashr_i32 s17, s17, 31
	v_mov_b32_e32 v135, v134
	v_pk_mul_f32 v[180:181], v[140:141], v[124:125]
	v_mul_f32_e32 v148, 0x4f7ffffe, v148
	v_cvt_u32_f32_e32 v148, v148
	v_pk_mul_f32 v[182:183], v[134:135], v[126:127]
	v_readfirstlane_b32 s19, v148
	s_mul_i32 s18, s18, s19
	s_mul_hi_u32 s18, s19, s18
	s_add_i32 s19, s19, s18
	s_mul_hi_u32 s18, s16, s19
	s_mul_i32 s19, s18, s13
	s_sub_i32 s16, s16, s19
	s_add_i32 s28, s18, 1
	s_sub_i32 s19, s16, s13
	s_cmp_ge_u32 s16, s13
	s_cselect_b32 s18, s28, s18
	s_cselect_b32 s16, s19, s16
	s_add_i32 s19, s18, 1
	s_cmp_ge_u32 s16, s13
	s_cselect_b32 s13, s19, s18
	s_xor_b32 s13, s13, s17
	s_sub_i32 s16, s13, s17
	s_ashr_i32 s17, s16, 31
	s_lshl_b64 s[16:17], s[16:17], 20
	v_lshl_add_u64 v[148:149], v[138:139], 0, s[16:17]
	v_lshl_add_u64 v[148:149], v[146:147], 2, v[148:149]
	global_store_dwordx4 v[148:149], v[180:183], off
	v_add_co_u32_e32 v150, vcc, s44, v148
	s_nop 0
	v_pk_mul_f32 v[182:183], v[134:135], v[122:123]
	v_pk_mul_f32 v[180:181], v[140:141], v[120:121]
	global_store_dwordx4 v[148:149], v[180:183], off offset:64
	v_addc_co_u32_e32 v151, vcc, 0, v149, vcc
	s_nop 0
	v_pk_mul_f32 v[182:183], v[134:135], v[118:119]
	v_pk_mul_f32 v[180:181], v[140:141], v[116:117]
	global_store_dwordx4 v[148:149], v[180:183], off offset:512
	s_mov_b32 s13, 0x20000
	s_nop 0
	v_pk_mul_f32 v[182:183], v[134:135], v[110:111]
	v_pk_mul_f32 v[180:181], v[140:141], v[108:109]
	global_store_dwordx4 v[148:149], v[180:183], off offset:576
	s_nop 1
	v_pk_mul_f32 v[182:183], v[134:135], v[114:115]
	v_pk_mul_f32 v[180:181], v[140:141], v[112:113]
	global_store_dwordx4 v[150:151], v[180:183], off
	s_nop 1
	v_pk_mul_f32 v[182:183], v[134:135], v[106:107]
	v_pk_mul_f32 v[180:181], v[140:141], v[104:105]
	global_store_dwordx4 v[150:151], v[180:183], off offset:64
	s_nop 1
	v_pk_mul_f32 v[182:183], v[134:135], v[102:103]
	v_pk_mul_f32 v[180:181], v[140:141], v[100:101]
	global_store_dwordx4 v[150:151], v[180:183], off offset:512
	s_nop 1
	v_pk_mul_f32 v[182:183], v[134:135], v[94:95]
	v_pk_mul_f32 v[180:181], v[140:141], v[92:93]
	global_store_dwordx4 v[150:151], v[180:183], off offset:576
	v_add_co_u32_e32 v150, vcc, s13, v148
	s_nop 0
	v_pk_mul_f32 v[182:183], v[134:135], v[98:99]
	v_pk_mul_f32 v[180:181], v[140:141], v[96:97]
	v_addc_co_u32_e32 v151, vcc, 0, v149, vcc
	global_store_dwordx4 v[150:151], v[180:183], off
	s_mov_b32 s13, 0x30000
	s_nop 0
	v_pk_mul_f32 v[182:183], v[134:135], v[90:91]
	v_pk_mul_f32 v[180:181], v[140:141], v[88:89]
	global_store_dwordx4 v[150:151], v[180:183], off offset:64
	s_nop 1
	v_pk_mul_f32 v[182:183], v[134:135], v[86:87]
	v_pk_mul_f32 v[180:181], v[140:141], v[84:85]
	global_store_dwordx4 v[150:151], v[180:183], off offset:512
	s_nop 1
	v_pk_mul_f32 v[182:183], v[134:135], v[78:79]
	v_pk_mul_f32 v[180:181], v[140:141], v[76:77]
	global_store_dwordx4 v[150:151], v[180:183], off offset:576
	v_add_co_u32_e32 v150, vcc, s13, v148
	s_nop 0
	v_pk_mul_f32 v[182:183], v[134:135], v[82:83]
	v_pk_mul_f32 v[180:181], v[140:141], v[80:81]
	v_addc_co_u32_e32 v151, vcc, 0, v149, vcc
	global_store_dwordx4 v[150:151], v[180:183], off
	s_mov_b32 s13, 0x80000
	s_nop 0
	v_pk_mul_f32 v[182:183], v[134:135], v[74:75]
	v_pk_mul_f32 v[180:181], v[140:141], v[72:73]
	global_store_dwordx4 v[150:151], v[180:183], off offset:64
	s_nop 1
	v_pk_mul_f32 v[182:183], v[134:135], v[70:71]
	v_pk_mul_f32 v[180:181], v[140:141], v[68:69]
	global_store_dwordx4 v[150:151], v[180:183], off offset:512
	s_nop 1
	v_pk_mul_f32 v[182:183], v[134:135], v[66:67]
	v_pk_mul_f32 v[180:181], v[140:141], v[64:65]
	global_store_dwordx4 v[150:151], v[180:183], off offset:576
	v_add_co_u32_e32 v150, vcc, s13, v148
	s_nop 0
	v_pk_mul_f32 v[182:183], v[134:135], v[62:63]
	v_pk_mul_f32 v[180:181], v[140:141], v[60:61]
	v_addc_co_u32_e32 v151, vcc, 0, v149, vcc
	global_store_dwordx4 v[150:151], v[180:183], off
	s_mov_b32 s13, 0x90000
	s_nop 0
	v_pk_mul_f32 v[182:183], v[134:135], v[58:59]
	v_pk_mul_f32 v[180:181], v[140:141], v[56:57]
	global_store_dwordx4 v[150:151], v[180:183], off offset:64
	s_nop 1
	v_pk_mul_f32 v[182:183], v[134:135], v[54:55]
	v_pk_mul_f32 v[180:181], v[140:141], v[52:53]
	global_store_dwordx4 v[150:151], v[180:183], off offset:512
	s_nop 1
	v_pk_mul_f32 v[182:183], v[134:135], v[46:47]
	v_pk_mul_f32 v[180:181], v[140:141], v[44:45]
	global_store_dwordx4 v[150:151], v[180:183], off offset:576
	v_add_co_u32_e32 v150, vcc, s13, v148
	s_nop 0
	v_pk_mul_f32 v[182:183], v[134:135], v[50:51]
	v_pk_mul_f32 v[180:181], v[140:141], v[48:49]
	v_addc_co_u32_e32 v151, vcc, 0, v149, vcc
	global_store_dwordx4 v[150:151], v[180:183], off
	s_mov_b32 s13, 0xa0000
	s_nop 0
	v_pk_mul_f32 v[182:183], v[134:135], v[42:43]
	v_pk_mul_f32 v[180:181], v[140:141], v[40:41]
	global_store_dwordx4 v[150:151], v[180:183], off offset:64
	s_nop 1
	v_pk_mul_f32 v[182:183], v[134:135], v[38:39]
	v_pk_mul_f32 v[180:181], v[140:141], v[36:37]
	global_store_dwordx4 v[150:151], v[180:183], off offset:512
	s_nop 1
	v_pk_mul_f32 v[182:183], v[134:135], v[30:31]
	v_pk_mul_f32 v[180:181], v[140:141], v[28:29]
	global_store_dwordx4 v[150:151], v[180:183], off offset:576
	v_add_co_u32_e32 v150, vcc, s13, v148
	s_nop 0
	v_pk_mul_f32 v[182:183], v[134:135], v[34:35]
	v_pk_mul_f32 v[180:181], v[140:141], v[32:33]
	v_addc_co_u32_e32 v151, vcc, 0, v149, vcc
	global_store_dwordx4 v[150:151], v[180:183], off
	s_mov_b32 s13, 0xb0000
	v_add_co_u32_e32 v184, vcc, s13, v148
	v_pk_mul_f32 v[182:183], v[134:135], v[26:27]
	v_pk_mul_f32 v[180:181], v[140:141], v[24:25]
	global_store_dwordx4 v[150:151], v[180:183], off offset:64
	v_addc_co_u32_e32 v185, vcc, 0, v149, vcc
	s_nop 0
	v_pk_mul_f32 v[182:183], v[134:135], v[22:23]
	v_pk_mul_f32 v[180:181], v[140:141], v[20:21]
	global_store_dwordx4 v[150:151], v[180:183], off offset:512
	v_pk_mul_f32 v[148:149], v[140:141], v[8:9]
	s_nop 0
	v_pk_mul_f32 v[182:183], v[134:135], v[14:15]
	v_pk_mul_f32 v[180:181], v[140:141], v[12:13]
	global_store_dwordx4 v[150:151], v[180:183], off offset:576
	v_pk_mul_f32 v[150:151], v[134:135], v[10:11]
	global_store_dwordx4 v[184:185], v[148:151], off offset:64
	v_pk_mul_f32 v[182:183], v[134:135], v[18:19]
	v_pk_mul_f32 v[180:181], v[140:141], v[16:17]
	v_pk_mul_f32 v[150:151], v[134:135], v[6:7]
	v_pk_mul_f32 v[148:149], v[140:141], v[4:5]
	global_store_dwordx4 v[184:185], v[148:151], off offset:512
	global_store_dwordx4 v[184:185], v[180:183], off
	s_nop 0
	v_pk_mul_f32 v[150:151], v[134:135], v[2:3]
	v_pk_mul_f32 v[148:149], v[140:141], v[0:1]
	global_store_dwordx4 v[184:185], v[148:151], off offset:576
	s_mov_b32 s92, s54
	s_movk_i32 s93, 0x2000
	s_cbranch_execnz .LBB0_788
	s_branch .LBB0_804

; #define PG8_STAGE(bufoff, gbase, voff) do { _Pragma("unroll") for (int _i = 0; _i < 2; ++_i) \
;         __builtin_amdgcn_global_load_lds((const unsigned*)((const char*)(gbase) + (voff)[_i]), (LAS unsigned*)(lds + (bufoff) + ldsw + _i * 8192), 16, 0, 0); } while (0)
; #define PG8_LDA(dst, b, h) do { _Pragma("unroll") for (int m = 0; m < 4; ++m) _Pragma("unroll") for (int k = 0; k < 2; ++k) dst[m][k] = *(const LAS bf16x8*)(lds + PG8_SA(b, h) + aoff + m * 2048 + k * 1024); } while (0)
; #define PG8_LDB(dst, b, h) do { _Pragma("unroll") for (int n = 0; n < 2; ++n) _Pragma("unroll") for (int k = 0; k < 2; ++k) dst[n][k] = *(const LAS bf16x8*)(lds + PG8_SB(b, h) + boff + n * 2048 + k * 1024); } while (0)
; #define PG8_MMA(ai, bj, At, Bt) do { __builtin_amdgcn_s_setprio(1); _Pragma("unroll") for (int m = 0; m < 4; ++m) _Pragma("unroll") for (int n = 0; n < 2; ++n) _Pragma("unroll") for (int k = 0; k < 2; ++k) \
;         acc[ai][bj][m][n] = __builtin_amdgcn_mfma_f32_16x16x32_bf16(Bt[n][k], At[m][k], acc[ai][bj][m][n], 0, 0, 0); __builtin_amdgcn_s_setprio(0); } while (0)
; #define PG8_WAIT_L(n) asm volatile("s_waitcnt lgkmcnt(" #n ")" ::: "memory")
; #define PG8_BAR __builtin_amdgcn_s_barrier()
; #define PG8_SCHED __builtin_amdgcn_sched_barrier(0)
; template <class Epi, class Sched>
; DI void gemm_phase(LAS unsigned char* lds, const Gemm g, const Sched& S, const Epi& E) {
;     ...
;             PG8_LDB(B0, 0, 0); PG8_SCHED; PG8_LDA(At, 0, 0); PG8_STAGE(PG8_SA(1, 1), a1 + hstep, voffA);
;             PG8_WAIT_L(8); PG8_BAR; PG8_WAIT_L(0); PG8_MMA(0, 0, At, B0); PG8_BAR; PG8_SCHED;
;             PG8_LDB(B1, 0, 1); PG8_STAGE(PG8_SB(0, 0), b2, voffB);
;             PG8_BAR; PG8_WAIT_L(0); PG8_MMA(0, 1, At, B1); PG8_BAR;
;             PG8_LDA(At, 0, 1); PG8_STAGE(PG8_SA(0, 0), a2, voffA);
;             PG8_BAR; PG8_WAIT_L(0); PG8_MMA(1, 0, At, B0); PG8_BAR; PG8_SCHED;
.LBB0_822:
	s_add_u32 s28, s18, 0xfffc0080
	s_addc_u32 s29, s19, -1
	s_add_i32 s78, 0, 0x10000
	v_add_u32_e32 v138, s78, v140
	ds_read_b128 v[144:147], v138
	ds_read_b128 v[148:151], v138 offset:1024
	ds_read_b128 v[178:181], v138 offset:2048
	ds_read_b128 v[182:185], v138 offset:3072
	s_cmp_eq_u32 s77, 12
	s_cselect_b32 s35, s13, s29
	s_cselect_b32 s34, s66, s28
	s_cselect_b32 s29, s11, s75
	s_cselect_b32 s28, s67, s74
	v_lshl_add_u64 v[138:139], s[18:19], 0, v[134:135]
	s_add_i32 m0, s37, 0xc000
	ds_read_b128 v[186:189], v142
	ds_read_b128 v[190:193], v142 offset:1024
	ds_read_b128 v[194:197], v142 offset:2048
	ds_read_b128 v[198:201], v142 offset:3072
	ds_read_b128 v[202:205], v142 offset:4096
	ds_read_b128 v[206:209], v142 offset:5120
	ds_read_b128 v[210:213], v142 offset:6144
	ds_read_b128 v[214:217], v142 offset:7168
	global_load_lds_dwordx4 v[138:139], off
	v_lshl_add_u64 v[138:139], s[18:19], 0, v[136:137]
	s_add_i32 m0, s37, 0xe000
	s_nop 0
	global_load_lds_dwordx4 v[138:139], off
	s_waitcnt lgkmcnt(8)
	s_barrier
	s_waitcnt lgkmcnt(0)
	s_setprio 1
	v_mfma_f32_16x16x32_bf16 v[120:123], v[144:147], v[186:189], v[120:123]
	v_mfma_f32_16x16x32_bf16 v[124:127], v[178:181], v[186:189], v[124:127]
	v_mfma_f32_16x16x32_bf16 v[104:107], v[144:147], v[194:197], v[104:107]
	v_mfma_f32_16x16x32_bf16 v[108:111], v[178:181], v[194:197], v[108:111]
	v_mfma_f32_16x16x32_bf16 v[88:91], v[144:147], v[202:205], v[88:91]
	v_mfma_f32_16x16x32_bf16 v[92:95], v[178:181], v[202:205], v[92:95]
	v_mfma_f32_16x16x32_bf16 v[72:75], v[144:147], v[210:213], v[72:75]
	v_mfma_f32_16x16x32_bf16 v[76:79], v[178:181], v[210:213], v[76:79]
	v_mfma_f32_16x16x32_bf16 v[120:123], v[148:151], v[190:193], v[120:123]
	v_mfma_f32_16x16x32_bf16 v[124:127], v[182:185], v[190:193], v[124:127]
	v_mfma_f32_16x16x32_bf16 v[104:107], v[148:151], v[198:201], v[104:107]
	v_mfma_f32_16x16x32_bf16 v[108:111], v[182:185], v[198:201], v[108:111]
	v_mfma_f32_16x16x32_bf16 v[88:91], v[148:151], v[206:209], v[88:91]
	v_mfma_f32_16x16x32_bf16 v[92:95], v[182:185], v[206:209], v[92:95]
	v_mfma_f32_16x16x32_bf16 v[72:75], v[148:151], v[214:217], v[72:75]
	v_mfma_f32_16x16x32_bf16 v[76:79], v[182:185], v[214:217], v[76:79]
	s_setprio 0
	s_barrier
	s_add_i32 s80, 0, 0x14000
	v_add_u32_e32 v138, s80, v140
	s_add_i32 s78, s78, s36
	ds_read_b128 v[218:221], v138
	ds_read_b128 v[222:225], v138 offset:1024
	ds_read_b128 v[226:229], v138 offset:2048
	ds_read_b128 v[230:233], v138 offset:3072
	v_lshl_add_u64 v[138:139], s[28:29], 0, v[128:129]
	s_mov_b32 m0, s78
	v_lshl_add_u64 v[234:235], s[28:29], 0, v[132:133]
	global_load_lds_dwordx4 v[138:139], off
	s_add_i32 m0, s78, 0x2000
	s_nop 0
	global_load_lds_dwordx4 v[234:235], off
	s_barrier
	s_waitcnt lgkmcnt(0)
	s_setprio 1
	v_mfma_f32_16x16x32_bf16 v[112:115], v[218:221], v[186:189], v[112:115]
	v_mfma_f32_16x16x32_bf16 v[116:119], v[226:229], v[186:189], v[116:119]
	v_mfma_f32_16x16x32_bf16 v[96:99], v[218:221], v[194:197], v[96:99]
	v_mfma_f32_16x16x32_bf16 v[100:103], v[226:229], v[194:197], v[100:103]
	v_mfma_f32_16x16x32_bf16 v[80:83], v[218:221], v[202:205], v[80:83]
	v_mfma_f32_16x16x32_bf16 v[84:87], v[226:229], v[202:205], v[84:87]
	v_mfma_f32_16x16x32_bf16 v[64:67], v[218:221], v[210:213], v[64:67]
	v_mfma_f32_16x16x32_bf16 v[68:71], v[226:229], v[210:213], v[68:71]
	v_mfma_f32_16x16x32_bf16 v[112:115], v[222:225], v[190:193], v[112:115]
	v_mfma_f32_16x16x32_bf16 v[116:119], v[230:233], v[190:193], v[116:119]
	v_mfma_f32_16x16x32_bf16 v[96:99], v[222:225], v[198:201], v[96:99]
	v_mfma_f32_16x16x32_bf16 v[100:103], v[230:233], v[198:201], v[100:103]
	v_mfma_f32_16x16x32_bf16 v[80:83], v[222:225], v[206:209], v[80:83]
	v_mfma_f32_16x16x32_bf16 v[84:87], v[230:233], v[206:209], v[84:87]
	v_mfma_f32_16x16x32_bf16 v[64:67], v[222:225], v[214:217], v[64:67]
	v_mfma_f32_16x16x32_bf16 v[68:71], v[230:233], v[214:217], v[68:71]
	s_setprio 0
	s_mov_b32 m0, s37
	v_lshl_add_u64 v[236:237], s[34:35], 0, v[128:129]
	s_barrier
	ds_read_b128 v[186:189], v142 offset:16384
	ds_read_b128 v[190:193], v142 offset:17408
	ds_read_b128 v[194:197], v142 offset:18432
	ds_read_b128 v[198:201], v142 offset:19456
	ds_read_b128 v[202:205], v142 offset:20480
	ds_read_b128 v[206:209], v142 offset:21504
	ds_read_b128 v[210:213], v142 offset:22528
	ds_read_b128 v[214:217], v142 offset:23552
	global_load_lds_dwordx4 v[236:237], off
	v_lshl_add_u64 v[238:239], s[34:35], 0, v[132:133]
	s_mov_b32 m0, s38
	s_nop 0
	global_load_lds_dwordx4 v[238:239], off
	s_barrier
	s_waitcnt lgkmcnt(0)
	s_setprio 1
	v_mfma_f32_16x16x32_bf16 v[56:59], v[144:147], v[186:189], v[56:59]
	v_mfma_f32_16x16x32_bf16 v[60:63], v[178:181], v[186:189], v[60:63]
	v_mfma_f32_16x16x32_bf16 v[40:43], v[144:147], v[194:197], v[40:43]
	v_mfma_f32_16x16x32_bf16 v[44:47], v[178:181], v[194:197], v[44:47]
	v_mfma_f32_16x16x32_bf16 v[24:27], v[144:147], v[202:205], v[24:27]
	v_mfma_f32_16x16x32_bf16 v[28:31], v[178:181], v[202:205], v[28:31]
	v_mfma_f32_16x16x32_bf16 v[8:11], v[144:147], v[210:213], v[8:11]
	v_mfma_f32_16x16x32_bf16 v[12:15], v[178:181], v[210:213], v[12:15]
	v_mfma_f32_16x16x32_bf16 v[56:59], v[148:151], v[190:193], v[56:59]
	v_mfma_f32_16x16x32_bf16 v[60:63], v[182:185], v[190:193], v[60:63]
	v_mfma_f32_16x16x32_bf16 v[40:43], v[148:151], v[198:201], v[40:43]
	v_mfma_f32_16x16x32_bf16 v[44:47], v[182:185], v[198:201], v[44:47]
	v_mfma_f32_16x16x32_bf16 v[24:27], v[148:151], v[206:209], v[24:27]
	v_mfma_f32_16x16x32_bf16 v[28:31], v[182:185], v[206:209], v[28:31]
	v_mfma_f32_16x16x32_bf16 v[8:11], v[148:151], v[214:217], v[8:11]
	v_mfma_f32_16x16x32_bf16 v[12:15], v[182:185], v[214:217], v[12:15]
	s_setprio 0
	s_barrier
; #define PG8_STAGE(bufoff, gbase, voff) do { _Pragma("unroll") for (int _i = 0; _i < 2; ++_i) \
;         __builtin_amdgcn_global_load_lds((const unsigned*)((const char*)(gbase) + (voff)[_i]), (LAS unsigned*)(lds + (bufoff) + ldsw + _i * 8192), 16, 0, 0); } while (0)
; #define PG8_LDA(dst, b, h) do { _Pragma("unroll") for (int m = 0; m < 4; ++m) _Pragma("unroll") for (int k = 0; k < 2; ++k) dst[m][k] = *(const LAS bf16x8*)(lds + PG8_SA(b, h) + aoff + m * 2048 + k * 1024); } while (0)
; #define PG8_LDB(dst, b, h) do { _Pragma("unroll") for (int n = 0; n < 2; ++n) _Pragma("unroll") for (int k = 0; k < 2; ++k) dst[n][k] = *(const LAS bf16x8*)(lds + PG8_SB(b, h) + boff + n * 2048 + k * 1024); } while (0)
; #define PG8_MMA(ai, bj, At, Bt) do { __builtin_amdgcn_s_setprio(1); _Pragma("unroll") for (int m = 0; m < 4; ++m) _Pragma("unroll") for (int n = 0; n < 2; ++n) _Pragma("unroll") for (int k = 0; k < 2; ++k) \
;         acc[ai][bj][m][n] = __builtin_amdgcn_mfma_f32_16x16x32_bf16(Bt[n][k], At[m][k], acc[ai][bj][m][n], 0, 0, 0); __builtin_amdgcn_s_setprio(0); } while (0)
; #define PG8_WAIT_V(n) asm volatile("s_waitcnt vmcnt(" #n ")" ::: "memory")
; #define PG8_WAIT_L(n) asm volatile("s_waitcnt lgkmcnt(" #n ")" ::: "memory")
; #define PG8_BAR __builtin_amdgcn_s_barrier()
; #define PG8_SCHED __builtin_amdgcn_sched_barrier(0)
; template <class Epi, class Sched>
; DI void gemm_phase(LAS unsigned char* lds, const Gemm g, const Sched& S, const Epi& E) {
;     ...
;             PG8_STAGE(PG8_SB(0, 1), b2 + hstep, voffB);
;             PG8_WAIT_V(6); PG8_BAR; PG8_MMA(1, 1, At, B1); PG8_BAR;
;             PG8_LDB(B0, 1, 0); PG8_SCHED; PG8_LDA(At, 1, 0); PG8_STAGE(PG8_SA(0, 1), a2 + hstep, voffA);
;             PG8_WAIT_L(8); PG8_BAR; PG8_WAIT_L(0); PG8_MMA(0, 0, At, B0); PG8_BAR; PG8_SCHED;
;             PG8_LDB(B1, 1, 1); PG8_STAGE(PG8_SB(1, 0), b3, voffB);
;             PG8_BAR; PG8_WAIT_L(0); PG8_MMA(0, 1, At, B1); PG8_BAR;
;             PG8_LDA(At, 1, 1); PG8_STAGE(PG8_SA(1, 0), a3, voffA);
;             PG8_BAR; PG8_WAIT_L(0); PG8_MMA(1, 0, At, B0); PG8_BAR; PG8_SCHED;
	s_add_u32 s78, s28, 0x40000
	s_addc_u32 s79, s29, 0
	s_add_i32 s80, s80, s36
	v_lshl_add_u64 v[144:145], s[78:79], 0, v[128:129]
	s_mov_b32 m0, s80
	s_nop 0
	global_load_lds_dwordx4 v[144:145], off
	v_lshl_add_u64 v[144:145], s[78:79], 0, v[132:133]
	s_add_i32 m0, s80, 0x2000
	s_nop 0
	global_load_lds_dwordx4 v[144:145], off
	s_waitcnt vmcnt(6)
	s_barrier
	s_setprio 1
	v_mfma_f32_16x16x32_bf16 v[48:51], v[218:221], v[186:189], v[48:51]
	v_mfma_f32_16x16x32_bf16 v[52:55], v[226:229], v[186:189], v[52:55]
	v_mfma_f32_16x16x32_bf16 v[32:35], v[218:221], v[194:197], v[32:35]
	v_mfma_f32_16x16x32_bf16 v[36:39], v[226:229], v[194:197], v[36:39]
	v_mfma_f32_16x16x32_bf16 v[16:19], v[218:221], v[202:205], v[16:19]
	v_mfma_f32_16x16x32_bf16 v[20:23], v[226:229], v[202:205], v[20:23]
	v_mfma_f32_16x16x32_bf16 v[0:3], v[218:221], v[210:213], v[0:3]
	v_mfma_f32_16x16x32_bf16 v[4:7], v[226:229], v[210:213], v[4:7]
	v_mfma_f32_16x16x32_bf16 v[48:51], v[222:225], v[190:193], v[48:51]
	v_mfma_f32_16x16x32_bf16 v[52:55], v[230:233], v[190:193], v[52:55]
	v_mfma_f32_16x16x32_bf16 v[32:35], v[222:225], v[198:201], v[32:35]
	v_mfma_f32_16x16x32_bf16 v[36:39], v[230:233], v[198:201], v[36:39]
	v_mfma_f32_16x16x32_bf16 v[16:19], v[222:225], v[206:209], v[16:19]
	v_mfma_f32_16x16x32_bf16 v[20:23], v[230:233], v[206:209], v[20:23]
	v_mfma_f32_16x16x32_bf16 v[0:3], v[222:225], v[214:217], v[0:3]
	v_mfma_f32_16x16x32_bf16 v[4:7], v[230:233], v[214:217], v[4:7]
	s_setprio 0
	s_add_i32 s78, 0, 0x18000
	v_add_u32_e32 v143, s78, v140
	s_barrier
	ds_read_b128 v[144:147], v143
	ds_read_b128 v[148:151], v143 offset:1024
	ds_read_b128 v[178:181], v143 offset:2048
	ds_read_b128 v[182:185], v143 offset:3072
	s_add_u32 s34, s34, 0x40000
	s_addc_u32 s35, s35, 0
	s_mov_b32 m0, s39
	v_lshl_add_u64 v[218:219], s[34:35], 0, v[128:129]
	ds_read_b128 v[186:189], v142 offset:32768
	ds_read_b128 v[190:193], v142 offset:33792
	ds_read_b128 v[194:197], v142 offset:34816
	ds_read_b128 v[198:201], v142 offset:35840
	ds_read_b128 v[202:205], v142 offset:36864
	ds_read_b128 v[206:209], v142 offset:37888
	ds_read_b128 v[210:213], v142 offset:38912
	ds_read_b128 v[214:217], v142 offset:39936
	global_load_lds_dwordx4 v[218:219], off
	v_lshl_add_u64 v[218:219], s[34:35], 0, v[132:133]
	s_mov_b32 m0, s40
	s_nop 0
	global_load_lds_dwordx4 v[218:219], off
	s_waitcnt lgkmcnt(8)
	s_barrier
	s_waitcnt lgkmcnt(0)
	s_setprio 1
	v_mfma_f32_16x16x32_bf16 v[120:123], v[144:147], v[186:189], v[120:123]
	v_mfma_f32_16x16x32_bf16 v[124:127], v[178:181], v[186:189], v[124:127]
	v_mfma_f32_16x16x32_bf16 v[104:107], v[144:147], v[194:197], v[104:107]
	v_mfma_f32_16x16x32_bf16 v[108:111], v[178:181], v[194:197], v[108:111]
	v_mfma_f32_16x16x32_bf16 v[88:91], v[144:147], v[202:205], v[88:91]
	v_mfma_f32_16x16x32_bf16 v[92:95], v[178:181], v[202:205], v[92:95]
	v_mfma_f32_16x16x32_bf16 v[72:75], v[144:147], v[210:213], v[72:75]
	v_mfma_f32_16x16x32_bf16 v[76:79], v[178:181], v[210:213], v[76:79]
	v_mfma_f32_16x16x32_bf16 v[120:123], v[148:151], v[190:193], v[120:123]
	v_mfma_f32_16x16x32_bf16 v[124:127], v[182:185], v[190:193], v[124:127]
	v_mfma_f32_16x16x32_bf16 v[104:107], v[148:151], v[198:201], v[104:107]
	v_mfma_f32_16x16x32_bf16 v[108:111], v[182:185], v[198:201], v[108:111]
	v_mfma_f32_16x16x32_bf16 v[88:91], v[148:151], v[206:209], v[88:91]
	v_mfma_f32_16x16x32_bf16 v[92:95], v[182:185], v[206:209], v[92:95]
	v_mfma_f32_16x16x32_bf16 v[72:75], v[148:151], v[214:217], v[72:75]
	v_mfma_f32_16x16x32_bf16 v[76:79], v[182:185], v[214:217], v[76:79]
	s_setprio 0
	s_barrier
	s_add_i32 s34, 0, 0x1c000
	s_add_i32 s35, s78, s36
	v_add_u32_e32 v143, s34, v140
	v_lshl_add_u64 v[138:139], v[138:139], 0, s[88:89]
	s_mov_b32 m0, s35
	ds_read_b128 v[218:221], v143
	ds_read_b128 v[222:225], v143 offset:1024
	ds_read_b128 v[226:229], v143 offset:2048
	ds_read_b128 v[230:233], v143 offset:3072
	global_load_lds_dwordx4 v[138:139], off
	v_lshl_add_u64 v[138:139], v[234:235], 0, s[88:89]
	s_add_i32 m0, s35, 0x2000
	s_nop 0
	global_load_lds_dwordx4 v[138:139], off
	s_barrier
	s_waitcnt lgkmcnt(0)
	s_setprio 1
	v_mfma_f32_16x16x32_bf16 v[112:115], v[218:221], v[186:189], v[112:115]
	v_mfma_f32_16x16x32_bf16 v[116:119], v[226:229], v[186:189], v[116:119]
	v_mfma_f32_16x16x32_bf16 v[96:99], v[218:221], v[194:197], v[96:99]
	v_mfma_f32_16x16x32_bf16 v[100:103], v[226:229], v[194:197], v[100:103]
	v_mfma_f32_16x16x32_bf16 v[80:83], v[218:221], v[202:205], v[80:83]
	v_mfma_f32_16x16x32_bf16 v[84:87], v[226:229], v[202:205], v[84:87]
	v_mfma_f32_16x16x32_bf16 v[64:67], v[218:221], v[210:213], v[64:67]
	v_mfma_f32_16x16x32_bf16 v[68:71], v[226:229], v[210:213], v[68:71]
	v_mfma_f32_16x16x32_bf16 v[112:115], v[222:225], v[190:193], v[112:115]
	v_mfma_f32_16x16x32_bf16 v[116:119], v[230:233], v[190:193], v[116:119]
	v_mfma_f32_16x16x32_bf16 v[96:99], v[222:225], v[198:201], v[96:99]
	v_mfma_f32_16x16x32_bf16 v[100:103], v[230:233], v[198:201], v[100:103]
	v_mfma_f32_16x16x32_bf16 v[80:83], v[222:225], v[206:209], v[80:83]
	v_mfma_f32_16x16x32_bf16 v[84:87], v[230:233], v[206:209], v[84:87]
	v_mfma_f32_16x16x32_bf16 v[64:67], v[222:225], v[214:217], v[64:67]
	v_mfma_f32_16x16x32_bf16 v[68:71], v[230:233], v[214:217], v[68:71]
	s_setprio 0
	s_mov_b32 m0, s41
	v_lshl_add_u64 v[138:139], v[236:237], 0, s[88:89]
	s_barrier
	ds_read_b128 v[186:189], v142 offset:49152
	ds_read_b128 v[190:193], v142 offset:50176
	ds_read_b128 v[194:197], v142 offset:51200
	ds_read_b128 v[198:201], v142 offset:52224
	ds_read_b128 v[202:205], v142 offset:53248
	ds_read_b128 v[206:209], v142 offset:54272
	ds_read_b128 v[210:213], v142 offset:55296
	ds_read_b128 v[214:217], v142 offset:56320
	global_load_lds_dwordx4 v[138:139], off
	v_lshl_add_u64 v[138:139], v[238:239], 0, s[88:89]
	s_mov_b32 m0, s58
	s_nop 0
	global_load_lds_dwordx4 v[138:139], off
	s_barrier
; DI unsigned pk2(float a, float b) { f32x2 v = {a, b}; nbf2 r = __builtin_convertvector(v, nbf2); return __builtin_bit_cast(unsigned, r); }
; #define PG8_STAGE(bufoff, gbase, voff) do { _Pragma("unroll") for (int _i = 0; _i < 2; ++_i) \
;         __builtin_amdgcn_global_load_lds((const unsigned*)((const char*)(gbase) + (voff)[_i]), (LAS unsigned*)(lds + (bufoff) + ldsw + _i * 8192), 16, 0, 0); } while (0)
; #define PG8_WAIT_V(n) asm volatile("s_waitcnt vmcnt(" #n ")" ::: "memory")
; #define PG8_WAIT_L(n) asm volatile("s_waitcnt lgkmcnt(" #n ")" ::: "memory")
; #define PG8_BAR __builtin_amdgcn_s_barrier()
; #define PG8_SCHED __builtin_amdgcn_sched_barrier(0)
; template <class Epi, class Sched>
; DI void gemm_phase(LAS unsigned char* lds, const Gemm g, const Sched& S, const Epi& E) {
;     ...
;             PG8_BAR; PG8_WAIT_L(0); PG8_MMA(1, 0, At, B0); PG8_BAR; PG8_SCHED;
;             PG8_STAGE(PG8_SB(1, 1), b3 + hstep, voffB);
;             PG8_WAIT_V(6); PG8_BAR; PG8_MMA(1, 1, At, B1); PG8_BAR;
;         }
;     DI void operator()(const f32x4 (&acc)[2][2][4][2], const pg8::Unit& u, int wr, int wc, int fr, int fq) const {
;         const int row0 = u.pm * 256 + wr * 64 + fr, col0 = u.pn * 128 + wc * 32 + 8 * fq;
; #pragma unroll
;         for (int ai = 0; ai < 2; ++ai)
; #pragma unroll
;             for (int m = 0; m < 4; ++m) { bf16_t* rowp = H + (size_t)(row0 + ai * 128 + m * 16) * FF + col0;
;                 float h[8];
; #pragma unroll
;                 for (int bj = 0; bj < 2; ++bj)
; #pragma unroll
;                     for (int j = 0; j < 4; j += 2) { const f32x2 g2 = {acc[ai][bj][m][0][j], acc[ai][bj][m][0][j + 1]}, u2 = {acc[ai][bj][m][1][j], acc[ai][bj][m][1][j + 1]};
;                         const f32x2 t2 = g2 * (-1.4426950408889634f); f32x2 e2; e2[0] = __builtin_amdgcn_exp2f(t2[0]); e2[1] = __builtin_amdgcn_exp2f(t2[1]);
;                         const f32x2 d2 = e2 + 1.0f; f32x2 r2; r2[0] = __builtin_amdgcn_rcpf(d2[0]); r2[1] = __builtin_amdgcn_rcpf(d2[1]);
;                         const f32x2 h2 = (g2 * u2) * r2; h[bj * 4 + j] = h2[0]; h[bj * 4 + j + 1] = h2[1]; }
;                 u32x4 w; w.x = pk2(h[0], h[1]); w.y = pk2(h[2], h[3]); w.z = pk2(h[4], h[5]); w.w = pk2(h[6], h[7]);
;                 *(u32x4*)rowp = w; asm volatile("" ::: "memory"); }
	s_waitcnt lgkmcnt(0)
	s_setprio 1
	v_mfma_f32_16x16x32_bf16 v[56:59], v[144:147], v[186:189], v[56:59]
	v_mfma_f32_16x16x32_bf16 v[60:63], v[178:181], v[186:189], v[60:63]
	v_mfma_f32_16x16x32_bf16 v[40:43], v[144:147], v[194:197], v[40:43]
	v_mfma_f32_16x16x32_bf16 v[44:47], v[178:181], v[194:197], v[44:47]
	v_mfma_f32_16x16x32_bf16 v[24:27], v[144:147], v[202:205], v[24:27]
	v_mfma_f32_16x16x32_bf16 v[28:31], v[178:181], v[202:205], v[28:31]
	v_mfma_f32_16x16x32_bf16 v[8:11], v[144:147], v[210:213], v[8:11]
	v_mfma_f32_16x16x32_bf16 v[12:15], v[178:181], v[210:213], v[12:15]
	v_mfma_f32_16x16x32_bf16 v[56:59], v[148:151], v[190:193], v[56:59]
	v_mfma_f32_16x16x32_bf16 v[60:63], v[182:185], v[190:193], v[60:63]
	v_mfma_f32_16x16x32_bf16 v[40:43], v[148:151], v[198:201], v[40:43]
	v_mfma_f32_16x16x32_bf16 v[44:47], v[182:185], v[198:201], v[44:47]
	v_mfma_f32_16x16x32_bf16 v[24:27], v[148:151], v[206:209], v[24:27]
	v_mfma_f32_16x16x32_bf16 v[28:31], v[182:185], v[206:209], v[28:31]
	v_mfma_f32_16x16x32_bf16 v[8:11], v[148:151], v[214:217], v[8:11]
	v_mfma_f32_16x16x32_bf16 v[12:15], v[182:185], v[214:217], v[12:15]
	s_setprio 0
	s_barrier
	s_add_u32 s28, s28, 0x40080
	s_addc_u32 s29, s29, 0
	s_add_i32 s34, s34, s36
	v_lshl_add_u64 v[138:139], s[28:29], 0, v[128:129]
	s_mov_b32 m0, s34
	s_nop 0
	global_load_lds_dwordx4 v[138:139], off
	v_lshl_add_u64 v[138:139], s[28:29], 0, v[132:133]
	s_add_i32 m0, s34, 0x2000
	s_nop 0
	global_load_lds_dwordx4 v[138:139], off
	s_waitcnt vmcnt(6)
	s_barrier
	s_setprio 1
	v_mfma_f32_16x16x32_bf16 v[48:51], v[218:221], v[186:189], v[48:51]
	v_mfma_f32_16x16x32_bf16 v[52:55], v[226:229], v[186:189], v[52:55]
	v_mfma_f32_16x16x32_bf16 v[32:35], v[218:221], v[194:197], v[32:35]
	v_mfma_f32_16x16x32_bf16 v[36:39], v[226:229], v[194:197], v[36:39]
	v_mfma_f32_16x16x32_bf16 v[16:19], v[218:221], v[202:205], v[16:19]
	v_mfma_f32_16x16x32_bf16 v[20:23], v[226:229], v[202:205], v[20:23]
	v_mfma_f32_16x16x32_bf16 v[0:3], v[218:221], v[210:213], v[0:3]
	v_mfma_f32_16x16x32_bf16 v[4:7], v[226:229], v[210:213], v[4:7]
	v_mfma_f32_16x16x32_bf16 v[48:51], v[222:225], v[190:193], v[48:51]
	v_mfma_f32_16x16x32_bf16 v[52:55], v[230:233], v[190:193], v[52:55]
	v_mfma_f32_16x16x32_bf16 v[32:35], v[222:225], v[198:201], v[32:35]
	v_mfma_f32_16x16x32_bf16 v[36:39], v[230:233], v[198:201], v[36:39]
	v_mfma_f32_16x16x32_bf16 v[16:19], v[222:225], v[206:209], v[16:19]
	v_mfma_f32_16x16x32_bf16 v[20:23], v[230:233], v[206:209], v[20:23]
	v_mfma_f32_16x16x32_bf16 v[0:3], v[222:225], v[214:217], v[0:3]
	v_mfma_f32_16x16x32_bf16 v[4:7], v[230:233], v[214:217], v[4:7]
	s_setprio 0
	s_add_i32 s77, s77, 2
	s_add_u32 s18, s18, 0x100
	s_addc_u32 s19, s19, 0
	s_add_u32 s74, s74, 0x100
	s_addc_u32 s75, s75, 0
	s_cmp_gt_u32 s77, 13
	s_barrier
	s_cbranch_scc0 .LBB0_822
	v_pk_mul_f32 v[148:149], v[120:121], s[76:77] op_sel_hi:[1,0]
	v_pk_mul_f32 v[120:121], v[124:125], v[120:121]
	v_pk_mul_f32 v[124:125], v[112:113], s[76:77] op_sel_hi:[1,0]
	v_pk_mul_f32 v[112:113], v[116:117], v[112:113]
	v_exp_f32_e32 v124, v124
	v_exp_f32_e32 v125, v125
	v_pk_mul_f32 v[126:127], v[126:127], v[122:123]
	v_pk_mul_f32 v[122:123], v[122:123], s[76:77] op_sel_hi:[1,0]
	v_exp_f32_e32 v148, v148
	v_pk_add_f32 v[124:125], v[124:125], 1.0 op_sel_hi:[1,0]
	v_exp_f32_e32 v149, v149
	v_rcp_f32_e32 v124, v124
	v_rcp_f32_e32 v125, v125
	v_exp_f32_e32 v122, v122
	v_exp_f32_e32 v123, v123
	v_pk_add_f32 v[148:149], v[148:149], 1.0 op_sel_hi:[1,0]
	v_pk_mul_f32 v[116:117], v[112:113], v[124:125]
	v_pk_mul_f32 v[112:113], v[114:115], s[76:77] op_sel_hi:[1,0]
	v_pk_add_f32 v[122:123], v[122:123], 1.0 op_sel_hi:[1,0]
	v_exp_f32_e32 v112, v112
	v_exp_f32_e32 v113, v113
	v_rcp_f32_e32 v148, v148
	v_rcp_f32_e32 v149, v149
	v_rcp_f32_e32 v122, v122
	v_pk_add_f32 v[112:113], v[112:113], 1.0 op_sel_hi:[1,0]
	v_rcp_f32_e32 v123, v123
	v_rcp_f32_e32 v112, v112
	v_rcp_f32_e32 v113, v113
	v_lshl_or_b32 v144, s64, 7, v141
	v_lshl_add_u32 v143, s65, 8, v131
	v_ashrrev_i32_e32 v145, 31, v144
	v_mov_b64_e32 v[138:139], s[72:73]
	v_pk_mul_f32 v[118:119], v[118:119], v[114:115]
	v_mad_i64_i32 v[146:147], s[18:19], v143, s60, v[138:139]
	v_pk_mul_f32 v[120:121], v[120:121], v[148:149]
	v_pk_mul_f32 v[122:123], v[126:127], v[122:123]
	v_pk_mul_f32 v[118:119], v[118:119], v[112:113]
	v_lshlrev_b64 v[112:113], 1, v[144:145]
	v_lshl_add_u64 v[124:125], v[146:147], 0, v[112:113]
	v_cvt_pk_bf16_f32 v114, v120, v121
	v_cvt_pk_bf16_f32 v115, v122, v123
	v_cvt_pk_bf16_f32 v116, v116, v117
	v_cvt_pk_bf16_f32 v117, v118, v119
	global_store_dwordx4 v[124:125], v[114:117], off
	v_pk_mul_f32 v[110:111], v[110:111], v[106:107]
	v_pk_mul_f32 v[106:107], v[106:107], s[76:77] op_sel_hi:[1,0]
	v_pk_mul_f32 v[116:117], v[104:105], s[76:77] op_sel_hi:[1,0]
	v_pk_mul_f32 v[104:105], v[108:109], v[104:105]
	v_pk_mul_f32 v[108:109], v[96:97], s[76:77] op_sel_hi:[1,0]
	v_pk_mul_f32 v[96:97], v[100:101], v[96:97]
	v_exp_f32_e32 v108, v108
	v_exp_f32_e32 v109, v109
	v_exp_f32_e32 v116, v116
	v_exp_f32_e32 v117, v117
	v_exp_f32_e32 v106, v106
	v_pk_add_f32 v[108:109], v[108:109], 1.0 op_sel_hi:[1,0]
	v_exp_f32_e32 v107, v107
	v_rcp_f32_e32 v108, v108
	v_rcp_f32_e32 v109, v109
	v_pk_add_f32 v[116:117], v[116:117], 1.0 op_sel_hi:[1,0]
	v_pk_add_f32 v[106:107], v[106:107], 1.0 op_sel_hi:[1,0]
	v_rcp_f32_e32 v116, v116
	v_pk_mul_f32 v[100:101], v[96:97], v[108:109]
	v_pk_mul_f32 v[96:97], v[98:99], s[76:77] op_sel_hi:[1,0]
	v_rcp_f32_e32 v117, v117
	v_exp_f32_e32 v96, v96
	v_exp_f32_e32 v97, v97
	v_rcp_f32_e32 v106, v106
	v_rcp_f32_e32 v107, v107
	v_or_b32_e32 v114, 16, v143
	v_pk_add_f32 v[96:97], v[96:97], 1.0 op_sel_hi:[1,0]
; DI unsigned pk2(float a, float b) { f32x2 v = {a, b}; nbf2 r = __builtin_convertvector(v, nbf2); return __builtin_bit_cast(unsigned, r); }
;     DI void operator()(const f32x4 (&acc)[2][2][4][2], const pg8::Unit& u, int wr, int wc, int fr, int fq) const {
;     ...
;         for (int ai = 0; ai < 2; ++ai)
; #pragma unroll
;             for (int m = 0; m < 4; ++m) { bf16_t* rowp = H + (size_t)(row0 + ai * 128 + m * 16) * FF + col0;
;                 float h[8];
; #pragma unroll
;                 for (int bj = 0; bj < 2; ++bj)
; #pragma unroll
;                     for (int j = 0; j < 4; j += 2) { const f32x2 g2 = {acc[ai][bj][m][0][j], acc[ai][bj][m][0][j + 1]}, u2 = {acc[ai][bj][m][1][j], acc[ai][bj][m][1][j + 1]};
;                         const f32x2 t2 = g2 * (-1.4426950408889634f); f32x2 e2; e2[0] = __builtin_amdgcn_exp2f(t2[0]); e2[1] = __builtin_amdgcn_exp2f(t2[1]);
;                         const f32x2 d2 = e2 + 1.0f; f32x2 r2; r2[0] = __builtin_amdgcn_rcpf(d2[0]); r2[1] = __builtin_amdgcn_rcpf(d2[1]);
;                         const f32x2 h2 = (g2 * u2) * r2; h[bj * 4 + j] = h2[0]; h[bj * 4 + j + 1] = h2[1]; }
;                 u32x4 w; w.x = pk2(h[0], h[1]); w.y = pk2(h[2], h[3]); w.z = pk2(h[4], h[5]); w.w = pk2(h[6], h[7]);
;                 *(u32x4*)rowp = w; asm volatile("" ::: "memory"); }
	v_pk_mul_f32 v[102:103], v[102:103], v[98:99]
	v_rcp_f32_e32 v96, v96
	v_rcp_f32_e32 v97, v97
	v_mad_i64_i32 v[114:115], s[18:19], v114, s60, v[138:139]
	v_pk_mul_f32 v[104:105], v[104:105], v[116:117]
	v_pk_mul_f32 v[106:107], v[110:111], v[106:107]
	v_pk_mul_f32 v[102:103], v[102:103], v[96:97]
	v_lshl_add_u64 v[108:109], v[114:115], 0, v[112:113]
	v_cvt_pk_bf16_f32 v96, v104, v105
	v_cvt_pk_bf16_f32 v97, v106, v107
	v_cvt_pk_bf16_f32 v98, v100, v101
	v_cvt_pk_bf16_f32 v99, v102, v103
	global_store_dwordx4 v[108:109], v[96:99], off
	v_pk_mul_f32 v[94:95], v[94:95], v[90:91]
	v_pk_mul_f32 v[90:91], v[90:91], s[76:77] op_sel_hi:[1,0]
	v_pk_mul_f32 v[98:99], v[88:89], s[76:77] op_sel_hi:[1,0]
	v_pk_mul_f32 v[88:89], v[92:93], v[88:89]
	v_pk_mul_f32 v[92:93], v[80:81], s[76:77] op_sel_hi:[1,0]
	v_pk_mul_f32 v[80:81], v[84:85], v[80:81]
	v_exp_f32_e32 v92, v92
	v_exp_f32_e32 v93, v93
	v_exp_f32_e32 v98, v98
	v_exp_f32_e32 v99, v99
	v_exp_f32_e32 v90, v90
	v_pk_add_f32 v[92:93], v[92:93], 1.0 op_sel_hi:[1,0]
	v_exp_f32_e32 v91, v91
	v_rcp_f32_e32 v92, v92
	v_rcp_f32_e32 v93, v93
	v_pk_add_f32 v[98:99], v[98:99], 1.0 op_sel_hi:[1,0]
	v_pk_add_f32 v[90:91], v[90:91], 1.0 op_sel_hi:[1,0]
	v_rcp_f32_e32 v98, v98
	v_pk_mul_f32 v[84:85], v[80:81], v[92:93]
	v_pk_mul_f32 v[80:81], v[82:83], s[76:77] op_sel_hi:[1,0]
	v_rcp_f32_e32 v99, v99
	v_exp_f32_e32 v80, v80
	v_exp_f32_e32 v81, v81
	v_rcp_f32_e32 v90, v90
	v_rcp_f32_e32 v91, v91
	v_or_b32_e32 v96, 32, v143
	v_pk_add_f32 v[80:81], v[80:81], 1.0 op_sel_hi:[1,0]
	v_pk_mul_f32 v[86:87], v[86:87], v[82:83]
	v_rcp_f32_e32 v80, v80
	v_rcp_f32_e32 v81, v81
	v_mad_i64_i32 v[96:97], s[18:19], v96, s60, v[138:139]
	v_pk_mul_f32 v[88:89], v[88:89], v[98:99]
	v_pk_mul_f32 v[90:91], v[94:95], v[90:91]
	v_pk_mul_f32 v[86:87], v[86:87], v[80:81]
	v_lshl_add_u64 v[92:93], v[96:97], 0, v[112:113]
	v_cvt_pk_bf16_f32 v80, v88, v89
	v_cvt_pk_bf16_f32 v81, v90, v91
	v_cvt_pk_bf16_f32 v82, v84, v85
	v_cvt_pk_bf16_f32 v83, v86, v87
	global_store_dwordx4 v[92:93], v[80:83], off
	v_pk_mul_f32 v[78:79], v[78:79], v[74:75]
	v_pk_mul_f32 v[74:75], v[74:75], s[76:77] op_sel_hi:[1,0]
	v_pk_mul_f32 v[82:83], v[72:73], s[76:77] op_sel_hi:[1,0]
	v_pk_mul_f32 v[72:73], v[76:77], v[72:73]
	v_pk_mul_f32 v[76:77], v[64:65], s[76:77] op_sel_hi:[1,0]
	v_pk_mul_f32 v[64:65], v[68:69], v[64:65]
	v_exp_f32_e32 v76, v76
	v_exp_f32_e32 v77, v77
	v_exp_f32_e32 v82, v82
	v_exp_f32_e32 v83, v83
	v_exp_f32_e32 v74, v74
	v_pk_add_f32 v[76:77], v[76:77], 1.0 op_sel_hi:[1,0]
	v_exp_f32_e32 v75, v75
	v_rcp_f32_e32 v76, v76
	v_rcp_f32_e32 v77, v77
	v_pk_add_f32 v[82:83], v[82:83], 1.0 op_sel_hi:[1,0]
	v_pk_add_f32 v[74:75], v[74:75], 1.0 op_sel_hi:[1,0]
	v_rcp_f32_e32 v82, v82
	v_pk_mul_f32 v[68:69], v[64:65], v[76:77]
	v_pk_mul_f32 v[64:65], v[66:67], s[76:77] op_sel_hi:[1,0]
	v_rcp_f32_e32 v83, v83
	v_exp_f32_e32 v64, v64
	v_exp_f32_e32 v65, v65
	v_rcp_f32_e32 v74, v74
	v_rcp_f32_e32 v75, v75
	v_or_b32_e32 v80, 48, v143
	v_pk_add_f32 v[64:65], v[64:65], 1.0 op_sel_hi:[1,0]
	v_pk_mul_f32 v[70:71], v[70:71], v[66:67]
	v_rcp_f32_e32 v64, v64
	v_rcp_f32_e32 v65, v65
	v_mad_i64_i32 v[80:81], s[18:19], v80, s60, v[138:139]
	v_pk_mul_f32 v[72:73], v[72:73], v[82:83]
	v_pk_mul_f32 v[74:75], v[78:79], v[74:75]
	v_pk_mul_f32 v[70:71], v[70:71], v[64:65]
	v_lshl_add_u64 v[76:77], v[80:81], 0, v[112:113]
	v_cvt_pk_bf16_f32 v64, v72, v73
	v_cvt_pk_bf16_f32 v65, v74, v75
	v_cvt_pk_bf16_f32 v66, v68, v69
	v_cvt_pk_bf16_f32 v67, v70, v71
	global_store_dwordx4 v[76:77], v[64:67], off
	v_pk_mul_f32 v[62:63], v[62:63], v[58:59]
	v_pk_mul_f32 v[58:59], v[58:59], s[76:77] op_sel_hi:[1,0]
	v_pk_mul_f32 v[66:67], v[56:57], s[76:77] op_sel_hi:[1,0]
	v_pk_mul_f32 v[56:57], v[60:61], v[56:57]
	v_pk_mul_f32 v[60:61], v[48:49], s[76:77] op_sel_hi:[1,0]
	v_pk_mul_f32 v[48:49], v[52:53], v[48:49]
	v_exp_f32_e32 v60, v60
	v_exp_f32_e32 v61, v61
	v_exp_f32_e32 v66, v66
	v_exp_f32_e32 v67, v67
	v_exp_f32_e32 v58, v58
	v_pk_add_f32 v[60:61], v[60:61], 1.0 op_sel_hi:[1,0]
	v_exp_f32_e32 v59, v59
	v_rcp_f32_e32 v60, v60
	v_rcp_f32_e32 v61, v61
	v_pk_add_f32 v[66:67], v[66:67], 1.0 op_sel_hi:[1,0]
	v_pk_add_f32 v[58:59], v[58:59], 1.0 op_sel_hi:[1,0]
	v_rcp_f32_e32 v66, v66
	v_pk_mul_f32 v[52:53], v[48:49], v[60:61]
	v_pk_mul_f32 v[48:49], v[50:51], s[76:77] op_sel_hi:[1,0]
	v_rcp_f32_e32 v67, v67
	v_exp_f32_e32 v48, v48
	v_exp_f32_e32 v49, v49
	v_rcp_f32_e32 v58, v58
	v_rcp_f32_e32 v59, v59
	v_add_u32_e32 v64, 0x80, v143
	v_pk_add_f32 v[48:49], v[48:49], 1.0 op_sel_hi:[1,0]
	v_pk_mul_f32 v[54:55], v[54:55], v[50:51]
	v_rcp_f32_e32 v48, v48
	v_rcp_f32_e32 v49, v49
	v_mad_i64_i32 v[64:65], s[18:19], v64, s60, v[138:139]
	v_pk_mul_f32 v[56:57], v[56:57], v[66:67]
	v_pk_mul_f32 v[58:59], v[62:63], v[58:59]
	v_pk_mul_f32 v[54:55], v[54:55], v[48:49]
	v_lshl_add_u64 v[60:61], v[64:65], 0, v[112:113]
; DI unsigned pk2(float a, float b) { f32x2 v = {a, b}; nbf2 r = __builtin_convertvector(v, nbf2); return __builtin_bit_cast(unsigned, r); }
;     DI void operator()(const f32x4 (&acc)[2][2][4][2], const pg8::Unit& u, int wr, int wc, int fr, int fq) const {
;     ...
;         for (int ai = 0; ai < 2; ++ai)
; #pragma unroll
;             for (int m = 0; m < 4; ++m) { bf16_t* rowp = H + (size_t)(row0 + ai * 128 + m * 16) * FF + col0;
;                 float h[8];
; #pragma unroll
;                 for (int bj = 0; bj < 2; ++bj)
; #pragma unroll
;                     for (int j = 0; j < 4; j += 2) { const f32x2 g2 = {acc[ai][bj][m][0][j], acc[ai][bj][m][0][j + 1]}, u2 = {acc[ai][bj][m][1][j], acc[ai][bj][m][1][j + 1]};
;                         const f32x2 t2 = g2 * (-1.4426950408889634f); f32x2 e2; e2[0] = __builtin_amdgcn_exp2f(t2[0]); e2[1] = __builtin_amdgcn_exp2f(t2[1]);
;                         const f32x2 d2 = e2 + 1.0f; f32x2 r2; r2[0] = __builtin_amdgcn_rcpf(d2[0]); r2[1] = __builtin_amdgcn_rcpf(d2[1]);
;                         const f32x2 h2 = (g2 * u2) * r2; h[bj * 4 + j] = h2[0]; h[bj * 4 + j + 1] = h2[1]; }
;                 u32x4 w; w.x = pk2(h[0], h[1]); w.y = pk2(h[2], h[3]); w.z = pk2(h[4], h[5]); w.w = pk2(h[6], h[7]);
;                 *(u32x4*)rowp = w; asm volatile("" ::: "memory"); }
	v_cvt_pk_bf16_f32 v48, v56, v57
	v_cvt_pk_bf16_f32 v49, v58, v59
	v_cvt_pk_bf16_f32 v50, v52, v53
	v_cvt_pk_bf16_f32 v51, v54, v55
	global_store_dwordx4 v[60:61], v[48:51], off
	v_pk_mul_f32 v[46:47], v[46:47], v[42:43]
	v_pk_mul_f32 v[42:43], v[42:43], s[76:77] op_sel_hi:[1,0]
	v_pk_mul_f32 v[50:51], v[40:41], s[76:77] op_sel_hi:[1,0]
	v_pk_mul_f32 v[40:41], v[44:45], v[40:41]
	v_pk_mul_f32 v[44:45], v[32:33], s[76:77] op_sel_hi:[1,0]
	v_pk_mul_f32 v[32:33], v[36:37], v[32:33]
	v_exp_f32_e32 v44, v44
	v_exp_f32_e32 v45, v45
	v_exp_f32_e32 v50, v50
	v_exp_f32_e32 v51, v51
	v_exp_f32_e32 v42, v42
	v_pk_add_f32 v[44:45], v[44:45], 1.0 op_sel_hi:[1,0]
	v_exp_f32_e32 v43, v43
	v_rcp_f32_e32 v44, v44
	v_rcp_f32_e32 v45, v45
	v_pk_add_f32 v[50:51], v[50:51], 1.0 op_sel_hi:[1,0]
	v_pk_add_f32 v[42:43], v[42:43], 1.0 op_sel_hi:[1,0]
	v_rcp_f32_e32 v50, v50
	v_pk_mul_f32 v[36:37], v[32:33], v[44:45]
	v_pk_mul_f32 v[32:33], v[34:35], s[76:77] op_sel_hi:[1,0]
	v_rcp_f32_e32 v51, v51
	v_exp_f32_e32 v32, v32
	v_exp_f32_e32 v33, v33
	v_rcp_f32_e32 v42, v42
	v_rcp_f32_e32 v43, v43
	v_add_u32_e32 v48, 0x90, v143
	v_pk_add_f32 v[32:33], v[32:33], 1.0 op_sel_hi:[1,0]
	v_pk_mul_f32 v[38:39], v[38:39], v[34:35]
	v_rcp_f32_e32 v32, v32
	v_rcp_f32_e32 v33, v33
	v_mad_i64_i32 v[48:49], s[18:19], v48, s60, v[138:139]
	v_pk_mul_f32 v[40:41], v[40:41], v[50:51]
	v_pk_mul_f32 v[42:43], v[46:47], v[42:43]
	v_pk_mul_f32 v[38:39], v[38:39], v[32:33]
	v_lshl_add_u64 v[44:45], v[48:49], 0, v[112:113]
	v_cvt_pk_bf16_f32 v32, v40, v41
	v_cvt_pk_bf16_f32 v33, v42, v43
	v_cvt_pk_bf16_f32 v34, v36, v37
	v_cvt_pk_bf16_f32 v35, v38, v39
	global_store_dwordx4 v[44:45], v[32:35], off
	v_pk_mul_f32 v[30:31], v[30:31], v[26:27]
	v_pk_mul_f32 v[26:27], v[26:27], s[76:77] op_sel_hi:[1,0]
	v_pk_mul_f32 v[34:35], v[24:25], s[76:77] op_sel_hi:[1,0]
	v_pk_mul_f32 v[24:25], v[28:29], v[24:25]
	v_pk_mul_f32 v[28:29], v[16:17], s[76:77] op_sel_hi:[1,0]
	v_pk_mul_f32 v[16:17], v[20:21], v[16:17]
	v_exp_f32_e32 v28, v28
	v_exp_f32_e32 v29, v29
	v_exp_f32_e32 v34, v34
	v_exp_f32_e32 v35, v35
	v_exp_f32_e32 v26, v26
	v_pk_add_f32 v[28:29], v[28:29], 1.0 op_sel_hi:[1,0]
	v_exp_f32_e32 v27, v27
	v_rcp_f32_e32 v28, v28
	v_rcp_f32_e32 v29, v29
	v_pk_add_f32 v[34:35], v[34:35], 1.0 op_sel_hi:[1,0]
	v_pk_add_f32 v[26:27], v[26:27], 1.0 op_sel_hi:[1,0]
	v_rcp_f32_e32 v34, v34
	v_pk_mul_f32 v[20:21], v[16:17], v[28:29]
	v_pk_mul_f32 v[16:17], v[18:19], s[76:77] op_sel_hi:[1,0]
	v_rcp_f32_e32 v35, v35
	v_exp_f32_e32 v16, v16
	v_exp_f32_e32 v17, v17
	v_rcp_f32_e32 v26, v26
	v_rcp_f32_e32 v27, v27
	v_add_u32_e32 v32, 0xa0, v143
	v_pk_add_f32 v[16:17], v[16:17], 1.0 op_sel_hi:[1,0]
	v_pk_mul_f32 v[22:23], v[22:23], v[18:19]
	v_rcp_f32_e32 v16, v16
	v_rcp_f32_e32 v17, v17
	v_mad_i64_i32 v[32:33], s[18:19], v32, s60, v[138:139]
	v_pk_mul_f32 v[24:25], v[24:25], v[34:35]
	v_pk_mul_f32 v[26:27], v[30:31], v[26:27]
	v_pk_mul_f32 v[22:23], v[22:23], v[16:17]
	v_lshl_add_u64 v[28:29], v[32:33], 0, v[112:113]
	v_cvt_pk_bf16_f32 v16, v24, v25
	v_cvt_pk_bf16_f32 v17, v26, v27
	v_cvt_pk_bf16_f32 v18, v20, v21
	v_cvt_pk_bf16_f32 v19, v22, v23
	global_store_dwordx4 v[28:29], v[16:19], off
	v_pk_mul_f32 v[14:15], v[14:15], v[10:11]
	v_pk_mul_f32 v[10:11], v[10:11], s[76:77] op_sel_hi:[1,0]
	v_pk_mul_f32 v[18:19], v[8:9], s[76:77] op_sel_hi:[1,0]
	v_pk_mul_f32 v[8:9], v[12:13], v[8:9]
	v_pk_mul_f32 v[12:13], v[0:1], s[76:77] op_sel_hi:[1,0]
	v_pk_mul_f32 v[0:1], v[4:5], v[0:1]
	v_exp_f32_e32 v12, v12
	v_exp_f32_e32 v13, v13
	v_exp_f32_e32 v18, v18
	v_exp_f32_e32 v19, v19
	v_exp_f32_e32 v10, v10
	v_pk_add_f32 v[12:13], v[12:13], 1.0 op_sel_hi:[1,0]
	v_exp_f32_e32 v11, v11
	v_rcp_f32_e32 v12, v12
	v_rcp_f32_e32 v13, v13
	v_pk_add_f32 v[18:19], v[18:19], 1.0 op_sel_hi:[1,0]
	v_pk_add_f32 v[10:11], v[10:11], 1.0 op_sel_hi:[1,0]
	v_rcp_f32_e32 v18, v18
	v_pk_mul_f32 v[4:5], v[0:1], v[12:13]
	v_pk_mul_f32 v[0:1], v[2:3], s[76:77] op_sel_hi:[1,0]
	v_rcp_f32_e32 v19, v19
	v_exp_f32_e32 v0, v0
	v_exp_f32_e32 v1, v1
	v_rcp_f32_e32 v10, v10
	v_rcp_f32_e32 v11, v11
	v_add_u32_e32 v16, 0xb0, v143
	v_pk_add_f32 v[0:1], v[0:1], 1.0 op_sel_hi:[1,0]
	v_pk_mul_f32 v[6:7], v[6:7], v[2:3]
	v_rcp_f32_e32 v0, v0
	v_rcp_f32_e32 v1, v1
	v_mad_i64_i32 v[16:17], s[18:19], v16, s60, v[138:139]
	v_pk_mul_f32 v[8:9], v[8:9], v[18:19]
	v_pk_mul_f32 v[10:11], v[14:15], v[10:11]
	v_pk_mul_f32 v[6:7], v[6:7], v[0:1]
	v_lshl_add_u64 v[12:13], v[16:17], 0, v[112:113]
	v_cvt_pk_bf16_f32 v0, v8, v9
	v_cvt_pk_bf16_f32 v1, v10, v11
	v_cvt_pk_bf16_f32 v2, v4, v5
	v_cvt_pk_bf16_f32 v3, v6, v7
	global_store_dwordx4 v[12:13], v[0:3], off
	s_and_b64 vcc, exec, s[8:9]
	s_mov_b32 s64, s10
	s_mov_b32 s65, s12
	s_mov_b64 s[28:29], s[16:17]
	s_mov_b64 s[18:19], s[14:15]
	s_cbranch_vccz .LBB0_815
	s_waitcnt vmcnt(0)
	s_cmpk_gt_u32 s2, 0xff
	s_cbranch_scc1 .LBB0_826
	s_barrier
